# GEMM K-loops: two of the six staging loads of SP2(t) issued in the next 2-load segment instead (4/4 split), closing wait vmcnt(6)
# speedup vs baseline: 1.0140x; 1.0140x over previous
; #define PG8_STAGE(bufoff, gbase, voff) do { _Pragma("unroll") for (int _i = 0; _i < 2; ++_i) \
;         __builtin_amdgcn_global_load_lds((const unsigned*)((const char*)(gbase) + (voff)[_i]), (PG8_LAS unsigned*)(lds + (bufoff) + ldsw + _i * 8192), 16, 0, 0); } while (0)
; #define PG8_LDA(dst, b, h) do { _Pragma("unroll") for (int m = 0; m < 4; ++m) _Pragma("unroll") for (int k = 0; k < 2; ++k) dst[m][k] = *(const PG8_LAS bf16x8*)(lds + PG8_SA(b, h) + aoff + m * 2048 + k * 1024); } while (0)
; #define PG8_LDB(dst, b, h) do { _Pragma("unroll") for (int n = 0; n < 2; ++n) _Pragma("unroll") for (int k = 0; k < 2; ++k) dst[n][k] = *(const PG8_LAS bf16x8*)(lds + PG8_SB(b, h) + boff + n * 2048 + k * 1024); } while (0)
; #define PG8_MMA(ai, bj, At, Bt) do { __builtin_amdgcn_s_setprio(1); _Pragma("unroll") for (int m = 0; m < 4; ++m) _Pragma("unroll") for (int n = 0; n < 2; ++n) _Pragma("unroll") for (int k = 0; k < 2; ++k) \
;         acc[ai][bj][m][n] = __builtin_amdgcn_mfma_f32_16x16x32_bf16(Bt[n][k], At[m][k], acc[ai][bj][m][n], 0, 0, 0); __builtin_amdgcn_s_setprio(0); } while (0)
; #define PG8_WAIT_V(n) asm volatile("s_waitcnt vmcnt(" #n ")" ::: "memory")
; #define PG8_WAIT_L(n) asm volatile("s_waitcnt lgkmcnt(" #n ")" ::: "memory")
; #define PG8_BAR __builtin_amdgcn_s_barrier()
; #define PG8_SCHED __builtin_amdgcn_sched_barrier(0)
; template <class Epi, class Sched, bool ALIGN_EPI = false, bool SP2 = false>
; __device__ __forceinline__ void gemm_phase(PG8_LAS unsigned char* lds, const Gemm g, const Sched& S, const Epi& E) {
;     ...
;             PG8_LDB(B0, 0, 0); PG8_LDB(B1, 0, 1); PG8_SCHED; PG8_LDA(At, 0, 0); PG8_STAGE(PG8_SA(1, 1), a1 + hstep, voffA);
;             PG8_WAIT_V(8); PG8_WAIT_L(0); PG8_BAR; PG8_MMA(0, 0, At, B0); PG8_MMA(0, 1, At, B1); PG8_BAR; PG8_SCHED;
;             PG8_LDA(At, 0, 1); PG8_STAGE(PG8_SB(0, 0), b2, voffB); PG8_STAGE(PG8_SB(0, 1), b2 + hstep, voffB); PG8_STAGE(PG8_SA(0, 0), a2, voffA);
;             PG8_WAIT_V(8); PG8_WAIT_L(0); PG8_BAR; PG8_MMA(1, 0, At, B0); PG8_MMA(1, 1, At, B1); PG8_BAR; PG8_SCHED;
.LBB0_124:
	ds_read_b128 v[150:153], v161
	ds_read_b128 v[154:157], v161 offset:1024
	ds_read_b128 v[166:169], v161 offset:2048
	ds_read_b128 v[170:173], v161 offset:3072
	ds_read_b128 v[174:177], v162
	ds_read_b128 v[178:181], v162 offset:1024
	ds_read_b128 v[182:185], v162 offset:2048
	ds_read_b128 v[186:189], v162 offset:3072
	s_add_u32 s4, s36, 0xfff80080
	s_addc_u32 s5, s37, -1
	s_cmp_eq_u32 s69, 28
	s_cselect_b32 s41, s9, s5
	s_cselect_b32 s40, s27, s4
	s_cselect_b32 s39, s25, s68
	s_cselect_b32 s38, s35, s67
	s_add_i32 m0, s49, 0xc000
	ds_read_b128 v[190:193], v163
	ds_read_b128 v[194:197], v163 offset:1024
	ds_read_b128 v[198:201], v163 offset:2048
	ds_read_b128 v[202:205], v163 offset:3072
	ds_read_b128 v[206:209], v163 offset:4096
	ds_read_b128 v[210:213], v163 offset:5120
	ds_read_b128 v[214:217], v163 offset:6144
	ds_read_b128 v[218:221], v163 offset:7168
	global_load_lds_dwordx4 v140, s[36:37]
	s_add_i32 m0, s49, 0xe000
	s_nop 0
	global_load_lds_dwordx4 v142, s[36:37]
	s_waitcnt vmcnt(8)
	s_waitcnt lgkmcnt(0)
	s_barrier
	s_setprio 1
	s_waitcnt lgkmcnt(0)
	v_mfma_f32_16x16x32_bf16 v[126:129], v[150:153], v[190:193], v[126:129]
	v_mfma_f32_16x16x32_bf16 v[122:125], v[166:169], v[190:193], v[122:125]
	v_mfma_f32_16x16x32_bf16 v[110:113], v[150:153], v[198:201], v[110:113]
	v_mfma_f32_16x16x32_bf16 v[106:109], v[166:169], v[198:201], v[106:109]
	v_mfma_f32_16x16x32_bf16 v[94:97], v[150:153], v[206:209], v[94:97]
	v_mfma_f32_16x16x32_bf16 v[90:93], v[166:169], v[206:209], v[90:93]
	v_mfma_f32_16x16x32_bf16 v[78:81], v[150:153], v[214:217], v[78:81]
	v_mfma_f32_16x16x32_bf16 v[74:77], v[166:169], v[214:217], v[74:77]
	v_mfma_f32_16x16x32_bf16 v[126:129], v[154:157], v[194:197], v[126:129]
	v_mfma_f32_16x16x32_bf16 v[122:125], v[170:173], v[194:197], v[122:125]
	v_mfma_f32_16x16x32_bf16 v[110:113], v[154:157], v[202:205], v[110:113]
	v_mfma_f32_16x16x32_bf16 v[106:109], v[170:173], v[202:205], v[106:109]
	v_mfma_f32_16x16x32_bf16 v[94:97], v[154:157], v[210:213], v[94:97]
	v_mfma_f32_16x16x32_bf16 v[90:93], v[170:173], v[210:213], v[90:93]
	v_mfma_f32_16x16x32_bf16 v[78:81], v[154:157], v[218:221], v[78:81]
	v_mfma_f32_16x16x32_bf16 v[74:77], v[170:173], v[218:221], v[74:77]
	s_setprio 0
	s_setprio 1
	v_mfma_f32_16x16x32_bf16 v[118:121], v[174:177], v[190:193], v[118:121]
	v_mfma_f32_16x16x32_bf16 v[114:117], v[182:185], v[190:193], v[114:117]
	v_mfma_f32_16x16x32_bf16 v[102:105], v[174:177], v[198:201], v[102:105]
	v_mfma_f32_16x16x32_bf16 v[98:101], v[182:185], v[198:201], v[98:101]
	v_mfma_f32_16x16x32_bf16 v[86:89], v[174:177], v[206:209], v[86:89]
	v_mfma_f32_16x16x32_bf16 v[82:85], v[182:185], v[206:209], v[82:85]
	v_mfma_f32_16x16x32_bf16 v[70:73], v[174:177], v[214:217], v[70:73]
	v_mfma_f32_16x16x32_bf16 v[66:69], v[182:185], v[214:217], v[66:69]
	v_mfma_f32_16x16x32_bf16 v[118:121], v[178:181], v[194:197], v[118:121]
	v_mfma_f32_16x16x32_bf16 v[114:117], v[186:189], v[194:197], v[114:117]
	v_mfma_f32_16x16x32_bf16 v[102:105], v[178:181], v[202:205], v[102:105]
	v_mfma_f32_16x16x32_bf16 v[98:101], v[186:189], v[202:205], v[98:101]
	v_mfma_f32_16x16x32_bf16 v[86:89], v[178:181], v[210:213], v[86:89]
	v_mfma_f32_16x16x32_bf16 v[82:85], v[186:189], v[210:213], v[82:85]
	v_mfma_f32_16x16x32_bf16 v[70:73], v[178:181], v[218:221], v[70:73]
	v_mfma_f32_16x16x32_bf16 v[66:69], v[186:189], v[218:221], v[66:69]
	s_setprio 0
	s_barrier
	s_add_i32 s4, s64, s48
	s_mov_b32 m0, s4
	ds_read_b128 v[190:193], v163 offset:16384
	ds_read_b128 v[194:197], v163 offset:17408
	ds_read_b128 v[198:201], v163 offset:18432
	ds_read_b128 v[202:205], v163 offset:19456
	ds_read_b128 v[206:209], v163 offset:20480
	ds_read_b128 v[210:213], v163 offset:21504
	ds_read_b128 v[214:217], v163 offset:22528
	ds_read_b128 v[218:221], v163 offset:23552
	global_load_lds_dwordx4 v132, s[38:39]
	s_add_i32 m0, s4, 0x2000
	s_add_u32 s70, s38, 0x80000
	s_addc_u32 s71, s39, 0
	s_add_i32 s4, s65, s48
	global_load_lds_dwordx4 v136, s[38:39]
	s_mov_b32 m0, s4
	s_nop 0
	global_load_lds_dwordx4 v132, s[70:71]
	s_add_i32 m0, s4, 0x2000
	s_nop 0
	global_load_lds_dwordx4 v136, s[70:71]
	s_waitcnt vmcnt(6)
	s_waitcnt lgkmcnt(0)
	s_barrier
	s_setprio 1
	s_waitcnt lgkmcnt(0)
	v_mfma_f32_16x16x32_bf16 v[62:65], v[150:153], v[190:193], v[62:65]
	v_mfma_f32_16x16x32_bf16 v[58:61], v[166:169], v[190:193], v[58:61]
	v_mfma_f32_16x16x32_bf16 v[46:49], v[150:153], v[198:201], v[46:49]
	v_mfma_f32_16x16x32_bf16 v[42:45], v[166:169], v[198:201], v[42:45]
	v_mfma_f32_16x16x32_bf16 v[30:33], v[150:153], v[206:209], v[30:33]
	v_mfma_f32_16x16x32_bf16 v[26:29], v[166:169], v[206:209], v[26:29]
	v_mfma_f32_16x16x32_bf16 v[14:17], v[150:153], v[214:217], v[14:17]
	v_mfma_f32_16x16x32_bf16 v[10:13], v[166:169], v[214:217], v[10:13]
	v_mfma_f32_16x16x32_bf16 v[62:65], v[154:157], v[194:197], v[62:65]
	v_mfma_f32_16x16x32_bf16 v[58:61], v[170:173], v[194:197], v[58:61]
	v_mfma_f32_16x16x32_bf16 v[46:49], v[154:157], v[202:205], v[46:49]
	v_mfma_f32_16x16x32_bf16 v[42:45], v[170:173], v[202:205], v[42:45]
	v_mfma_f32_16x16x32_bf16 v[30:33], v[154:157], v[210:213], v[30:33]
	v_mfma_f32_16x16x32_bf16 v[26:29], v[170:173], v[210:213], v[26:29]
	v_mfma_f32_16x16x32_bf16 v[14:17], v[154:157], v[218:221], v[14:17]
	v_mfma_f32_16x16x32_bf16 v[10:13], v[170:173], v[218:221], v[10:13]
	s_setprio 0
	s_setprio 1
	v_mfma_f32_16x16x32_bf16 v[54:57], v[174:177], v[190:193], v[54:57]
	v_mfma_f32_16x16x32_bf16 v[50:53], v[182:185], v[190:193], v[50:53]
	v_mfma_f32_16x16x32_bf16 v[38:41], v[174:177], v[198:201], v[38:41]
	v_mfma_f32_16x16x32_bf16 v[34:37], v[182:185], v[198:201], v[34:37]
	v_mfma_f32_16x16x32_bf16 v[22:25], v[174:177], v[206:209], v[22:25]
	v_mfma_f32_16x16x32_bf16 v[18:21], v[182:185], v[206:209], v[18:21]
	v_mfma_f32_16x16x32_bf16 v[6:9], v[174:177], v[214:217], v[6:9]
	v_mfma_f32_16x16x32_bf16 v[2:5], v[182:185], v[214:217], v[2:5]
	v_mfma_f32_16x16x32_bf16 v[54:57], v[178:181], v[194:197], v[54:57]
	v_mfma_f32_16x16x32_bf16 v[50:53], v[186:189], v[194:197], v[50:53]
	v_mfma_f32_16x16x32_bf16 v[38:41], v[178:181], v[202:205], v[38:41]
	v_mfma_f32_16x16x32_bf16 v[34:37], v[186:189], v[202:205], v[34:37]
	v_mfma_f32_16x16x32_bf16 v[22:25], v[178:181], v[210:213], v[22:25]
	v_mfma_f32_16x16x32_bf16 v[18:21], v[186:189], v[210:213], v[18:21]
	v_mfma_f32_16x16x32_bf16 v[6:9], v[178:181], v[218:221], v[6:9]
	v_mfma_f32_16x16x32_bf16 v[2:5], v[186:189], v[218:221], v[2:5]
	s_setprio 0
	s_barrier
; #define PG8_STAGE(bufoff, gbase, voff) do { _Pragma("unroll") for (int _i = 0; _i < 2; ++_i) \
;         __builtin_amdgcn_global_load_lds((const unsigned*)((const char*)(gbase) + (voff)[_i]), (PG8_LAS unsigned*)(lds + (bufoff) + ldsw + _i * 8192), 16, 0, 0); } while (0)
; #define PG8_LDA(dst, b, h) do { _Pragma("unroll") for (int m = 0; m < 4; ++m) _Pragma("unroll") for (int k = 0; k < 2; ++k) dst[m][k] = *(const PG8_LAS bf16x8*)(lds + PG8_SA(b, h) + aoff + m * 2048 + k * 1024); } while (0)
; #define PG8_LDB(dst, b, h) do { _Pragma("unroll") for (int n = 0; n < 2; ++n) _Pragma("unroll") for (int k = 0; k < 2; ++k) dst[n][k] = *(const PG8_LAS bf16x8*)(lds + PG8_SB(b, h) + boff + n * 2048 + k * 1024); } while (0)
; #define PG8_MMA(ai, bj, At, Bt) do { __builtin_amdgcn_s_setprio(1); _Pragma("unroll") for (int m = 0; m < 4; ++m) _Pragma("unroll") for (int n = 0; n < 2; ++n) _Pragma("unroll") for (int k = 0; k < 2; ++k) \
;         acc[ai][bj][m][n] = __builtin_amdgcn_mfma_f32_16x16x32_bf16(Bt[n][k], At[m][k], acc[ai][bj][m][n], 0, 0, 0); __builtin_amdgcn_s_setprio(0); } while (0)
; #define PG8_WAIT_V(n) asm volatile("s_waitcnt vmcnt(" #n ")" ::: "memory")
; #define PG8_WAIT_L(n) asm volatile("s_waitcnt lgkmcnt(" #n ")" ::: "memory")
; #define PG8_BAR __builtin_amdgcn_s_barrier()
; template <class Epi, class Sched, bool ALIGN_EPI = false, bool SP2 = false>
; __device__ __forceinline__ void gemm_phase(PG8_LAS unsigned char* lds, const Gemm g, const Sched& S, const Epi& E) {
;     ...
;         for (int t = 0; t < nt; t += 2) {
;             const bool last = (t == nt - 2);
;             const char* a1 = cA + (size_t)(t + 1) * kstep;
;             const char* a2 = last ? nA : cA + (size_t)(t + 2) * kstep; const char* b2 = last ? nB : cB + (size_t)(t + 2) * kstep;
;             const char* a3 = a2 + kstep; const char* b3 = b2 + kstep;
;     ...
;             PG8_LDB(B0, 1, 0); PG8_LDB(B1, 1, 1); PG8_SCHED; PG8_LDA(At, 1, 0); PG8_STAGE(PG8_SA(0, 1), a2 + hstep, voffA);
;             PG8_WAIT_V(8); PG8_WAIT_L(0); PG8_BAR; PG8_MMA(0, 0, At, B0); PG8_MMA(0, 1, At, B1); PG8_BAR; PG8_SCHED;
;             PG8_LDA(At, 1, 1); PG8_STAGE(PG8_SB(1, 0), b3, voffB); PG8_STAGE(PG8_SB(1, 1), b3 + hstep, voffB); PG8_STAGE(PG8_SA(1, 0), a3, voffA);
;             PG8_WAIT_V(8); PG8_WAIT_L(0); PG8_BAR; PG8_MMA(1, 0, At, B0); PG8_MMA(1, 1, At, B1); PG8_BAR; PG8_SCHED;
	s_add_i32 s4, 0, 0x18000
	v_add_u32_e32 v138, s4, v159
	s_add_i32 s5, 0, 0x1c000
	ds_read_b128 v[150:153], v138
	ds_read_b128 v[154:157], v138 offset:1024
	ds_read_b128 v[166:169], v138 offset:2048
	ds_read_b128 v[170:173], v138 offset:3072
	v_add_u32_e32 v138, s5, v159
	ds_read_b128 v[174:177], v138
	ds_read_b128 v[178:181], v138 offset:1024
	ds_read_b128 v[182:185], v138 offset:2048
	ds_read_b128 v[186:189], v138 offset:3072
	s_add_u32 s70, s40, 0x80000
	s_addc_u32 s71, s41, 0
	s_mov_b32 m0, s49
	s_nop 0
	global_load_lds_dwordx4 v130, s[40:41]
	s_mov_b32 m0, s50
	s_nop 0
	global_load_lds_dwordx4 v134, s[40:41]
	s_mov_b32 m0, s51
	ds_read_b128 v[190:193], v163 offset:32768
	ds_read_b128 v[194:197], v163 offset:33792
	ds_read_b128 v[198:201], v163 offset:34816
	ds_read_b128 v[202:205], v163 offset:35840
	ds_read_b128 v[206:209], v163 offset:36864
	ds_read_b128 v[210:213], v163 offset:37888
	ds_read_b128 v[214:217], v163 offset:38912
	ds_read_b128 v[218:221], v163 offset:39936
	global_load_lds_dwordx4 v130, s[70:71]
	s_mov_b32 m0, s52
	s_nop 0
	global_load_lds_dwordx4 v134, s[70:71]
	s_waitcnt vmcnt(8)
	s_waitcnt lgkmcnt(0)
	s_barrier
	s_setprio 1
	s_waitcnt lgkmcnt(0)
	v_mfma_f32_16x16x32_bf16 v[126:129], v[150:153], v[190:193], v[126:129]
	v_mfma_f32_16x16x32_bf16 v[122:125], v[166:169], v[190:193], v[122:125]
	v_mfma_f32_16x16x32_bf16 v[110:113], v[150:153], v[198:201], v[110:113]
	v_mfma_f32_16x16x32_bf16 v[106:109], v[166:169], v[198:201], v[106:109]
	v_mfma_f32_16x16x32_bf16 v[94:97], v[150:153], v[206:209], v[94:97]
	v_mfma_f32_16x16x32_bf16 v[90:93], v[166:169], v[206:209], v[90:93]
	v_mfma_f32_16x16x32_bf16 v[78:81], v[150:153], v[214:217], v[78:81]
	v_mfma_f32_16x16x32_bf16 v[74:77], v[166:169], v[214:217], v[74:77]
	v_mfma_f32_16x16x32_bf16 v[126:129], v[154:157], v[194:197], v[126:129]
	v_mfma_f32_16x16x32_bf16 v[122:125], v[170:173], v[194:197], v[122:125]
	v_mfma_f32_16x16x32_bf16 v[110:113], v[154:157], v[202:205], v[110:113]
	v_mfma_f32_16x16x32_bf16 v[106:109], v[170:173], v[202:205], v[106:109]
	v_mfma_f32_16x16x32_bf16 v[94:97], v[154:157], v[210:213], v[94:97]
	v_mfma_f32_16x16x32_bf16 v[90:93], v[170:173], v[210:213], v[90:93]
	v_mfma_f32_16x16x32_bf16 v[78:81], v[154:157], v[218:221], v[78:81]
	v_mfma_f32_16x16x32_bf16 v[74:77], v[170:173], v[218:221], v[74:77]
	s_setprio 0
	s_setprio 1
	v_mfma_f32_16x16x32_bf16 v[118:121], v[174:177], v[190:193], v[118:121]
	v_mfma_f32_16x16x32_bf16 v[114:117], v[182:185], v[190:193], v[114:117]
	v_mfma_f32_16x16x32_bf16 v[102:105], v[174:177], v[198:201], v[102:105]
	v_mfma_f32_16x16x32_bf16 v[98:101], v[182:185], v[198:201], v[98:101]
	v_mfma_f32_16x16x32_bf16 v[86:89], v[174:177], v[206:209], v[86:89]
	v_mfma_f32_16x16x32_bf16 v[82:85], v[182:185], v[206:209], v[82:85]
	v_mfma_f32_16x16x32_bf16 v[70:73], v[174:177], v[214:217], v[70:73]
	v_mfma_f32_16x16x32_bf16 v[66:69], v[182:185], v[214:217], v[66:69]
	v_mfma_f32_16x16x32_bf16 v[118:121], v[178:181], v[194:197], v[118:121]
	v_mfma_f32_16x16x32_bf16 v[114:117], v[186:189], v[194:197], v[114:117]
	v_mfma_f32_16x16x32_bf16 v[102:105], v[178:181], v[202:205], v[102:105]
	v_mfma_f32_16x16x32_bf16 v[98:101], v[186:189], v[202:205], v[98:101]
	v_mfma_f32_16x16x32_bf16 v[86:89], v[178:181], v[210:213], v[86:89]
	v_mfma_f32_16x16x32_bf16 v[82:85], v[186:189], v[210:213], v[82:85]
	v_mfma_f32_16x16x32_bf16 v[70:73], v[178:181], v[218:221], v[70:73]
	v_mfma_f32_16x16x32_bf16 v[66:69], v[186:189], v[218:221], v[66:69]
	s_setprio 0
	s_barrier
	s_add_i32 s4, s4, s48
	s_add_i32 m0, s4, 0xffffff80
	ds_read_b128 v[190:193], v163 offset:49152
	ds_read_b128 v[194:197], v163 offset:50176
	ds_read_b128 v[198:201], v163 offset:51200
	ds_read_b128 v[202:205], v163 offset:52224
	ds_read_b128 v[206:209], v163 offset:53248
	ds_read_b128 v[210:213], v163 offset:54272
	ds_read_b128 v[214:217], v163 offset:55296
	ds_read_b128 v[218:221], v163 offset:56320
	global_load_lds_dwordx4 v132, s[38:39] offset:128
	s_add_i32 m0, s4, 0x1f80
	s_nop 0
	global_load_lds_dwordx4 v136, s[38:39] offset:128
	s_add_u32 s38, s38, 0x80080
	s_addc_u32 s39, s39, 0
	s_add_i32 s4, s5, s48
	s_mov_b32 m0, s4
	s_nop 0
	global_load_lds_dwordx4 v132, s[38:39]
	s_add_i32 m0, s4, 0x2000
	s_nop 0
	global_load_lds_dwordx4 v136, s[38:39]
	s_add_i32 m0, s58, 0xffffff80
	s_nop 0
	global_load_lds_dwordx4 v130, s[40:41] offset:128
	s_add_i32 m0, s59, 0xffffff80
	s_nop 0
	global_load_lds_dwordx4 v134, s[40:41] offset:128
	s_waitcnt vmcnt(8)
	s_waitcnt lgkmcnt(0)
	s_barrier
	s_setprio 1
	s_waitcnt lgkmcnt(0)
	v_mfma_f32_16x16x32_bf16 v[62:65], v[150:153], v[190:193], v[62:65]
	v_mfma_f32_16x16x32_bf16 v[58:61], v[166:169], v[190:193], v[58:61]
	v_mfma_f32_16x16x32_bf16 v[46:49], v[150:153], v[198:201], v[46:49]
	v_mfma_f32_16x16x32_bf16 v[42:45], v[166:169], v[198:201], v[42:45]
	v_mfma_f32_16x16x32_bf16 v[30:33], v[150:153], v[206:209], v[30:33]
	v_mfma_f32_16x16x32_bf16 v[26:29], v[166:169], v[206:209], v[26:29]
	v_mfma_f32_16x16x32_bf16 v[14:17], v[150:153], v[214:217], v[14:17]
	v_mfma_f32_16x16x32_bf16 v[10:13], v[166:169], v[214:217], v[10:13]
	v_mfma_f32_16x16x32_bf16 v[62:65], v[154:157], v[194:197], v[62:65]
	v_mfma_f32_16x16x32_bf16 v[58:61], v[170:173], v[194:197], v[58:61]
	v_mfma_f32_16x16x32_bf16 v[46:49], v[154:157], v[202:205], v[46:49]
	v_mfma_f32_16x16x32_bf16 v[42:45], v[170:173], v[202:205], v[42:45]
	v_mfma_f32_16x16x32_bf16 v[30:33], v[154:157], v[210:213], v[30:33]
	v_mfma_f32_16x16x32_bf16 v[26:29], v[170:173], v[210:213], v[26:29]
	v_mfma_f32_16x16x32_bf16 v[14:17], v[154:157], v[218:221], v[14:17]
	v_mfma_f32_16x16x32_bf16 v[10:13], v[170:173], v[218:221], v[10:13]
	s_setprio 0
	s_setprio 1
	v_mfma_f32_16x16x32_bf16 v[54:57], v[174:177], v[190:193], v[54:57]
	v_mfma_f32_16x16x32_bf16 v[50:53], v[182:185], v[190:193], v[50:53]
	v_mfma_f32_16x16x32_bf16 v[38:41], v[174:177], v[198:201], v[38:41]
	v_mfma_f32_16x16x32_bf16 v[34:37], v[182:185], v[198:201], v[34:37]
	v_mfma_f32_16x16x32_bf16 v[22:25], v[174:177], v[206:209], v[22:25]
	v_mfma_f32_16x16x32_bf16 v[18:21], v[182:185], v[206:209], v[18:21]
	v_mfma_f32_16x16x32_bf16 v[6:9], v[174:177], v[214:217], v[6:9]
	v_mfma_f32_16x16x32_bf16 v[2:5], v[182:185], v[214:217], v[2:5]
	v_mfma_f32_16x16x32_bf16 v[54:57], v[178:181], v[194:197], v[54:57]
	v_mfma_f32_16x16x32_bf16 v[50:53], v[186:189], v[194:197], v[50:53]
	v_mfma_f32_16x16x32_bf16 v[38:41], v[178:181], v[202:205], v[38:41]
	v_mfma_f32_16x16x32_bf16 v[34:37], v[186:189], v[202:205], v[34:37]
	v_mfma_f32_16x16x32_bf16 v[22:25], v[178:181], v[210:213], v[22:25]
	v_mfma_f32_16x16x32_bf16 v[18:21], v[186:189], v[210:213], v[18:21]
	v_mfma_f32_16x16x32_bf16 v[6:9], v[178:181], v[218:221], v[6:9]
	v_mfma_f32_16x16x32_bf16 v[2:5], v[186:189], v[218:221], v[2:5]
	s_setprio 0
	s_barrier
	s_add_i32 s69, s69, 2
	s_add_u32 s36, s36, 0x100
	s_addc_u32 s37, s37, 0
	s_add_u32 s67, s67, 0x100
	s_addc_u32 s68, s68, 0
	s_cmp_gt_u32 s69, 29
	s_cbranch_scc0 .LBB0_124
	s_and_b64 vcc, exec, s[22:23]
	s_cbranch_vccz .LBB0_127
	s_barrier

; #define PG8_STAGE(bufoff, gbase, voff) do { _Pragma("unroll") for (int _i = 0; _i < 2; ++_i) \
;         __builtin_amdgcn_global_load_lds((const unsigned*)((const char*)(gbase) + (voff)[_i]), (PG8_LAS unsigned*)(lds + (bufoff) + ldsw + _i * 8192), 16, 0, 0); } while (0)
; #define PG8_LDA(dst, b, h) do { _Pragma("unroll") for (int m = 0; m < 4; ++m) _Pragma("unroll") for (int k = 0; k < 2; ++k) dst[m][k] = *(const PG8_LAS bf16x8*)(lds + PG8_SA(b, h) + aoff + m * 2048 + k * 1024); } while (0)
; #define PG8_LDB(dst, b, h) do { _Pragma("unroll") for (int n = 0; n < 2; ++n) _Pragma("unroll") for (int k = 0; k < 2; ++k) dst[n][k] = *(const PG8_LAS bf16x8*)(lds + PG8_SB(b, h) + boff + n * 2048 + k * 1024); } while (0)
; #define PG8_MMA(ai, bj, At, Bt) do { __builtin_amdgcn_s_setprio(1); _Pragma("unroll") for (int m = 0; m < 4; ++m) _Pragma("unroll") for (int n = 0; n < 2; ++n) _Pragma("unroll") for (int k = 0; k < 2; ++k) \
;         acc[ai][bj][m][n] = __builtin_amdgcn_mfma_f32_16x16x32_bf16(Bt[n][k], At[m][k], acc[ai][bj][m][n], 0, 0, 0); __builtin_amdgcn_s_setprio(0); } while (0)
; #define PG8_WAIT_V(n) asm volatile("s_waitcnt vmcnt(" #n ")" ::: "memory")
; #define PG8_WAIT_L(n) asm volatile("s_waitcnt lgkmcnt(" #n ")" ::: "memory")
; #define PG8_BAR __builtin_amdgcn_s_barrier()
; #define PG8_SCHED __builtin_amdgcn_sched_barrier(0)
; template <class Epi, class Sched, bool ALIGN_EPI = false, bool SP2 = false>
; __device__ __forceinline__ void gemm_phase(PG8_LAS unsigned char* lds, const Gemm g, const Sched& S, const Epi& E) {
;     ...
;             PG8_LDB(B0, 0, 0); PG8_LDB(B1, 0, 1); PG8_SCHED; PG8_LDA(At, 0, 0); PG8_STAGE(PG8_SA(1, 1), a1 + hstep, voffA);
;             PG8_WAIT_V(8); PG8_WAIT_L(0); PG8_BAR; PG8_MMA(0, 0, At, B0); PG8_MMA(0, 1, At, B1); PG8_BAR; PG8_SCHED;
;             PG8_LDA(At, 0, 1); PG8_STAGE(PG8_SB(0, 0), b2, voffB); PG8_STAGE(PG8_SB(0, 1), b2 + hstep, voffB); PG8_STAGE(PG8_SA(0, 0), a2, voffA);
;             PG8_WAIT_V(8); PG8_WAIT_L(0); PG8_BAR; PG8_MMA(1, 0, At, B0); PG8_MMA(1, 1, At, B1); PG8_BAR; PG8_SCHED;
.LBB0_763:
	ds_read_b128 v[154:157], v150
	ds_read_b128 v[158:161], v150 offset:1024
	ds_read_b128 v[162:165], v150 offset:2048
	ds_read_b128 v[166:169], v150 offset:3072
	ds_read_b128 v[170:173], v151
	ds_read_b128 v[174:177], v151 offset:1024
	ds_read_b128 v[178:181], v151 offset:2048
	ds_read_b128 v[182:185], v151 offset:3072
	s_add_u32 s4, s40, 0xfff80080
	s_addc_u32 s5, s41, -1
	s_cmp_eq_u32 s78, 28
	s_cselect_b32 s51, s31, s5
	s_cselect_b32 s50, s74, s4
	s_cselect_b32 s49, s29, s77
	s_cselect_b32 s48, s75, s76
	s_add_i32 m0, s39, 0xc000
	ds_read_b128 v[186:189], v152
	ds_read_b128 v[190:193], v152 offset:1024
	ds_read_b128 v[194:197], v152 offset:2048
	ds_read_b128 v[198:201], v152 offset:3072
	ds_read_b128 v[202:205], v152 offset:4096
	ds_read_b128 v[206:209], v152 offset:5120
	ds_read_b128 v[210:213], v152 offset:6144
	ds_read_b128 v[214:217], v152 offset:7168
	global_load_lds_dwordx4 v138, s[40:41]
	s_add_i32 m0, s39, 0xe000
	s_nop 0
	global_load_lds_dwordx4 v140, s[40:41]
	s_waitcnt vmcnt(8)
	s_waitcnt lgkmcnt(0)
	s_barrier
	s_setprio 1
	s_waitcnt lgkmcnt(0)
	v_mfma_f32_16x16x32_bf16 v[126:129], v[154:157], v[186:189], v[126:129]
	v_mfma_f32_16x16x32_bf16 v[122:125], v[162:165], v[186:189], v[122:125]
	v_mfma_f32_16x16x32_bf16 v[114:117], v[154:157], v[194:197], v[114:117]
	v_mfma_f32_16x16x32_bf16 v[106:109], v[162:165], v[194:197], v[106:109]
	v_mfma_f32_16x16x32_bf16 v[98:101], v[154:157], v[202:205], v[98:101]
	v_mfma_f32_16x16x32_bf16 v[90:93], v[162:165], v[202:205], v[90:93]
	v_mfma_f32_16x16x32_bf16 v[82:85], v[154:157], v[210:213], v[82:85]
	v_mfma_f32_16x16x32_bf16 v[74:77], v[162:165], v[210:213], v[74:77]
	v_mfma_f32_16x16x32_bf16 v[126:129], v[158:161], v[190:193], v[126:129]
	v_mfma_f32_16x16x32_bf16 v[122:125], v[166:169], v[190:193], v[122:125]
	v_mfma_f32_16x16x32_bf16 v[114:117], v[158:161], v[198:201], v[114:117]
	v_mfma_f32_16x16x32_bf16 v[106:109], v[166:169], v[198:201], v[106:109]
	v_mfma_f32_16x16x32_bf16 v[98:101], v[158:161], v[206:209], v[98:101]
	v_mfma_f32_16x16x32_bf16 v[90:93], v[166:169], v[206:209], v[90:93]
	v_mfma_f32_16x16x32_bf16 v[82:85], v[158:161], v[214:217], v[82:85]
	v_mfma_f32_16x16x32_bf16 v[74:77], v[166:169], v[214:217], v[74:77]
	s_setprio 0
	s_setprio 1
	v_mfma_f32_16x16x32_bf16 v[118:121], v[170:173], v[186:189], v[118:121]
	v_mfma_f32_16x16x32_bf16 v[110:113], v[178:181], v[186:189], v[110:113]
	v_mfma_f32_16x16x32_bf16 v[102:105], v[170:173], v[194:197], v[102:105]
	v_mfma_f32_16x16x32_bf16 v[94:97], v[178:181], v[194:197], v[94:97]
	v_mfma_f32_16x16x32_bf16 v[86:89], v[170:173], v[202:205], v[86:89]
	v_mfma_f32_16x16x32_bf16 v[78:81], v[178:181], v[202:205], v[78:81]
	v_mfma_f32_16x16x32_bf16 v[70:73], v[170:173], v[210:213], v[70:73]
	v_mfma_f32_16x16x32_bf16 v[66:69], v[178:181], v[210:213], v[66:69]
	v_mfma_f32_16x16x32_bf16 v[118:121], v[174:177], v[190:193], v[118:121]
	v_mfma_f32_16x16x32_bf16 v[110:113], v[182:185], v[190:193], v[110:113]
	v_mfma_f32_16x16x32_bf16 v[102:105], v[174:177], v[198:201], v[102:105]
	v_mfma_f32_16x16x32_bf16 v[94:97], v[182:185], v[198:201], v[94:97]
	v_mfma_f32_16x16x32_bf16 v[86:89], v[174:177], v[206:209], v[86:89]
	v_mfma_f32_16x16x32_bf16 v[78:81], v[182:185], v[206:209], v[78:81]
	v_mfma_f32_16x16x32_bf16 v[70:73], v[174:177], v[214:217], v[70:73]
	v_mfma_f32_16x16x32_bf16 v[66:69], v[182:185], v[214:217], v[66:69]
	s_setprio 0
	s_barrier
	s_add_i32 s4, s67, s58
	s_mov_b32 m0, s4
	ds_read_b128 v[186:189], v152 offset:16384
	ds_read_b128 v[190:193], v152 offset:17408
	ds_read_b128 v[194:197], v152 offset:18432
	ds_read_b128 v[198:201], v152 offset:19456
	ds_read_b128 v[202:205], v152 offset:20480
	ds_read_b128 v[206:209], v152 offset:21504
	ds_read_b128 v[210:213], v152 offset:22528
	ds_read_b128 v[214:217], v152 offset:23552
	global_load_lds_dwordx4 v132, s[48:49]
	s_add_i32 m0, s4, 0x2000
	s_add_u32 s4, s48, 0x80000
	s_addc_u32 s5, s49, 0
	s_add_i32 s79, s68, s58
	global_load_lds_dwordx4 v136, s[48:49]
	s_mov_b32 m0, s79
	s_nop 0
	global_load_lds_dwordx4 v132, s[4:5]
	s_add_i32 m0, s79, 0x2000
	s_nop 0
	global_load_lds_dwordx4 v136, s[4:5]
	s_waitcnt vmcnt(6)
	s_waitcnt lgkmcnt(0)
	s_barrier
	s_setprio 1
	s_waitcnt lgkmcnt(0)
	v_mfma_f32_16x16x32_bf16 v[62:65], v[154:157], v[186:189], v[62:65]
	v_mfma_f32_16x16x32_bf16 v[58:61], v[162:165], v[186:189], v[58:61]
	v_mfma_f32_16x16x32_bf16 v[50:53], v[154:157], v[194:197], v[50:53]
	v_mfma_f32_16x16x32_bf16 v[42:45], v[162:165], v[194:197], v[42:45]
	v_mfma_f32_16x16x32_bf16 v[34:37], v[154:157], v[202:205], v[34:37]
	v_mfma_f32_16x16x32_bf16 v[26:29], v[162:165], v[202:205], v[26:29]
	v_mfma_f32_16x16x32_bf16 v[18:21], v[154:157], v[210:213], v[18:21]
	v_mfma_f32_16x16x32_bf16 v[10:13], v[162:165], v[210:213], v[10:13]
	v_mfma_f32_16x16x32_bf16 v[62:65], v[158:161], v[190:193], v[62:65]
	v_mfma_f32_16x16x32_bf16 v[58:61], v[166:169], v[190:193], v[58:61]
	v_mfma_f32_16x16x32_bf16 v[50:53], v[158:161], v[198:201], v[50:53]
	v_mfma_f32_16x16x32_bf16 v[42:45], v[166:169], v[198:201], v[42:45]
	v_mfma_f32_16x16x32_bf16 v[34:37], v[158:161], v[206:209], v[34:37]
	v_mfma_f32_16x16x32_bf16 v[26:29], v[166:169], v[206:209], v[26:29]
	v_mfma_f32_16x16x32_bf16 v[18:21], v[158:161], v[214:217], v[18:21]
	v_mfma_f32_16x16x32_bf16 v[10:13], v[166:169], v[214:217], v[10:13]
	s_setprio 0
	s_setprio 1
	v_mfma_f32_16x16x32_bf16 v[54:57], v[170:173], v[186:189], v[54:57]
	v_mfma_f32_16x16x32_bf16 v[46:49], v[178:181], v[186:189], v[46:49]
	v_mfma_f32_16x16x32_bf16 v[38:41], v[170:173], v[194:197], v[38:41]
	v_mfma_f32_16x16x32_bf16 v[30:33], v[178:181], v[194:197], v[30:33]
	v_mfma_f32_16x16x32_bf16 v[22:25], v[170:173], v[202:205], v[22:25]
	v_mfma_f32_16x16x32_bf16 v[14:17], v[178:181], v[202:205], v[14:17]
	v_mfma_f32_16x16x32_bf16 v[6:9], v[170:173], v[210:213], v[6:9]
	v_mfma_f32_16x16x32_bf16 v[2:5], v[178:181], v[210:213], v[2:5]
	v_mfma_f32_16x16x32_bf16 v[54:57], v[174:177], v[190:193], v[54:57]
	v_mfma_f32_16x16x32_bf16 v[46:49], v[182:185], v[190:193], v[46:49]
	v_mfma_f32_16x16x32_bf16 v[38:41], v[174:177], v[198:201], v[38:41]
	v_mfma_f32_16x16x32_bf16 v[30:33], v[182:185], v[198:201], v[30:33]
	v_mfma_f32_16x16x32_bf16 v[22:25], v[174:177], v[206:209], v[22:25]
	v_mfma_f32_16x16x32_bf16 v[14:17], v[182:185], v[206:209], v[14:17]
	v_mfma_f32_16x16x32_bf16 v[6:9], v[174:177], v[214:217], v[6:9]
	v_mfma_f32_16x16x32_bf16 v[2:5], v[182:185], v[214:217], v[2:5]
	s_setprio 0
	s_barrier
; #define PG8_STAGE(bufoff, gbase, voff) do { _Pragma("unroll") for (int _i = 0; _i < 2; ++_i) \
;         __builtin_amdgcn_global_load_lds((const unsigned*)((const char*)(gbase) + (voff)[_i]), (PG8_LAS unsigned*)(lds + (bufoff) + ldsw + _i * 8192), 16, 0, 0); } while (0)
; #define PG8_LDA(dst, b, h) do { _Pragma("unroll") for (int m = 0; m < 4; ++m) _Pragma("unroll") for (int k = 0; k < 2; ++k) dst[m][k] = *(const PG8_LAS bf16x8*)(lds + PG8_SA(b, h) + aoff + m * 2048 + k * 1024); } while (0)
; #define PG8_LDB(dst, b, h) do { _Pragma("unroll") for (int n = 0; n < 2; ++n) _Pragma("unroll") for (int k = 0; k < 2; ++k) dst[n][k] = *(const PG8_LAS bf16x8*)(lds + PG8_SB(b, h) + boff + n * 2048 + k * 1024); } while (0)
; #define PG8_MMA(ai, bj, At, Bt) do { __builtin_amdgcn_s_setprio(1); _Pragma("unroll") for (int m = 0; m < 4; ++m) _Pragma("unroll") for (int n = 0; n < 2; ++n) _Pragma("unroll") for (int k = 0; k < 2; ++k) \
;         acc[ai][bj][m][n] = __builtin_amdgcn_mfma_f32_16x16x32_bf16(Bt[n][k], At[m][k], acc[ai][bj][m][n], 0, 0, 0); __builtin_amdgcn_s_setprio(0); } while (0)
; #define PG8_WAIT_V(n) asm volatile("s_waitcnt vmcnt(" #n ")" ::: "memory")
; #define PG8_WAIT_L(n) asm volatile("s_waitcnt lgkmcnt(" #n ")" ::: "memory")
; #define PG8_BAR __builtin_amdgcn_s_barrier()
; template <class Epi, class Sched, bool ALIGN_EPI = false, bool SP2 = false>
; __device__ __forceinline__ void gemm_phase(PG8_LAS unsigned char* lds, const Gemm g, const Sched& S, const Epi& E) {
;     ...
;         for (int t = 0; t < nt; t += 2) {
;             const bool last = (t == nt - 2);
;             const char* a1 = cA + (size_t)(t + 1) * kstep;
;             const char* a2 = last ? nA : cA + (size_t)(t + 2) * kstep; const char* b2 = last ? nB : cB + (size_t)(t + 2) * kstep;
;             const char* a3 = a2 + kstep; const char* b3 = b2 + kstep;
;     ...
;             PG8_LDB(B0, 1, 0); PG8_LDB(B1, 1, 1); PG8_SCHED; PG8_LDA(At, 1, 0); PG8_STAGE(PG8_SA(0, 1), a2 + hstep, voffA);
;             PG8_WAIT_V(8); PG8_WAIT_L(0); PG8_BAR; PG8_MMA(0, 0, At, B0); PG8_MMA(0, 1, At, B1); PG8_BAR; PG8_SCHED;
;             PG8_LDA(At, 1, 1); PG8_STAGE(PG8_SB(1, 0), b3, voffB); PG8_STAGE(PG8_SB(1, 1), b3 + hstep, voffB); PG8_STAGE(PG8_SA(1, 0), a3, voffA);
;             PG8_WAIT_V(8); PG8_WAIT_L(0); PG8_BAR; PG8_MMA(1, 0, At, B0); PG8_MMA(1, 1, At, B1); PG8_BAR; PG8_SCHED;
	s_add_i32 s79, 0, 0x18000
	v_add_u32_e32 v153, s79, v148
	s_add_i32 s80, 0, 0x1c000
	ds_read_b128 v[154:157], v153
	ds_read_b128 v[158:161], v153 offset:1024
	ds_read_b128 v[162:165], v153 offset:2048
	ds_read_b128 v[166:169], v153 offset:3072
	v_add_u32_e32 v153, s80, v148
	ds_read_b128 v[170:173], v153
	ds_read_b128 v[174:177], v153 offset:1024
	ds_read_b128 v[178:181], v153 offset:2048
	ds_read_b128 v[182:185], v153 offset:3072
	s_add_u32 s4, s50, 0x80000
	s_addc_u32 s5, s51, 0
	s_mov_b32 m0, s39
	s_nop 0
	global_load_lds_dwordx4 v130, s[50:51]
	s_mov_b32 m0, s59
	s_nop 0
	global_load_lds_dwordx4 v134, s[50:51]
	s_mov_b32 m0, s60
	ds_read_b128 v[186:189], v152 offset:32768
	ds_read_b128 v[190:193], v152 offset:33792
	ds_read_b128 v[194:197], v152 offset:34816
	ds_read_b128 v[198:201], v152 offset:35840
	ds_read_b128 v[202:205], v152 offset:36864
	ds_read_b128 v[206:209], v152 offset:37888
	ds_read_b128 v[210:213], v152 offset:38912
	ds_read_b128 v[214:217], v152 offset:39936
	global_load_lds_dwordx4 v130, s[4:5]
	s_mov_b32 m0, s61
	s_nop 0
	global_load_lds_dwordx4 v134, s[4:5]
	s_waitcnt vmcnt(8)
	s_waitcnt lgkmcnt(0)
	s_barrier
	s_setprio 1
	s_waitcnt lgkmcnt(0)
	v_mfma_f32_16x16x32_bf16 v[126:129], v[154:157], v[186:189], v[126:129]
	v_mfma_f32_16x16x32_bf16 v[122:125], v[162:165], v[186:189], v[122:125]
	v_mfma_f32_16x16x32_bf16 v[114:117], v[154:157], v[194:197], v[114:117]
	v_mfma_f32_16x16x32_bf16 v[106:109], v[162:165], v[194:197], v[106:109]
	v_mfma_f32_16x16x32_bf16 v[98:101], v[154:157], v[202:205], v[98:101]
	v_mfma_f32_16x16x32_bf16 v[90:93], v[162:165], v[202:205], v[90:93]
	v_mfma_f32_16x16x32_bf16 v[82:85], v[154:157], v[210:213], v[82:85]
	v_mfma_f32_16x16x32_bf16 v[74:77], v[162:165], v[210:213], v[74:77]
	v_mfma_f32_16x16x32_bf16 v[126:129], v[158:161], v[190:193], v[126:129]
	v_mfma_f32_16x16x32_bf16 v[122:125], v[166:169], v[190:193], v[122:125]
	v_mfma_f32_16x16x32_bf16 v[114:117], v[158:161], v[198:201], v[114:117]
	v_mfma_f32_16x16x32_bf16 v[106:109], v[166:169], v[198:201], v[106:109]
	v_mfma_f32_16x16x32_bf16 v[98:101], v[158:161], v[206:209], v[98:101]
	v_mfma_f32_16x16x32_bf16 v[90:93], v[166:169], v[206:209], v[90:93]
	v_mfma_f32_16x16x32_bf16 v[82:85], v[158:161], v[214:217], v[82:85]
	v_mfma_f32_16x16x32_bf16 v[74:77], v[166:169], v[214:217], v[74:77]
	s_setprio 0
	s_setprio 1
	v_mfma_f32_16x16x32_bf16 v[118:121], v[170:173], v[186:189], v[118:121]
	v_mfma_f32_16x16x32_bf16 v[110:113], v[178:181], v[186:189], v[110:113]
	v_mfma_f32_16x16x32_bf16 v[102:105], v[170:173], v[194:197], v[102:105]
	v_mfma_f32_16x16x32_bf16 v[94:97], v[178:181], v[194:197], v[94:97]
	v_mfma_f32_16x16x32_bf16 v[86:89], v[170:173], v[202:205], v[86:89]
	v_mfma_f32_16x16x32_bf16 v[78:81], v[178:181], v[202:205], v[78:81]
	v_mfma_f32_16x16x32_bf16 v[70:73], v[170:173], v[210:213], v[70:73]
	v_mfma_f32_16x16x32_bf16 v[66:69], v[178:181], v[210:213], v[66:69]
	v_mfma_f32_16x16x32_bf16 v[118:121], v[174:177], v[190:193], v[118:121]
	v_mfma_f32_16x16x32_bf16 v[110:113], v[182:185], v[190:193], v[110:113]
	v_mfma_f32_16x16x32_bf16 v[102:105], v[174:177], v[198:201], v[102:105]
	v_mfma_f32_16x16x32_bf16 v[94:97], v[182:185], v[198:201], v[94:97]
	v_mfma_f32_16x16x32_bf16 v[86:89], v[174:177], v[206:209], v[86:89]
	v_mfma_f32_16x16x32_bf16 v[78:81], v[182:185], v[206:209], v[78:81]
	v_mfma_f32_16x16x32_bf16 v[70:73], v[174:177], v[214:217], v[70:73]
	v_mfma_f32_16x16x32_bf16 v[66:69], v[182:185], v[214:217], v[66:69]
	s_setprio 0
	s_barrier
	s_add_i32 s4, s79, s58
	s_add_i32 m0, s4, 0xffffff80
	ds_read_b128 v[186:189], v152 offset:49152
	ds_read_b128 v[190:193], v152 offset:50176
	ds_read_b128 v[194:197], v152 offset:51200
	ds_read_b128 v[198:201], v152 offset:52224
	ds_read_b128 v[202:205], v152 offset:53248
	ds_read_b128 v[206:209], v152 offset:54272
	ds_read_b128 v[210:213], v152 offset:55296
	ds_read_b128 v[214:217], v152 offset:56320
	global_load_lds_dwordx4 v132, s[48:49] offset:128
	s_add_i32 m0, s4, 0x1f80
	s_add_u32 s4, s48, 0x80080
	s_addc_u32 s5, s49, 0
	global_load_lds_dwordx4 v136, s[48:49] offset:128
	s_add_i32 s48, s80, s58
	s_mov_b32 m0, s48
	s_nop 0
	global_load_lds_dwordx4 v132, s[4:5]
	s_add_i32 m0, s48, 0x2000
	s_nop 0
	global_load_lds_dwordx4 v136, s[4:5]
	s_add_i32 m0, s63, 0xffffff80
	s_nop 0
	global_load_lds_dwordx4 v130, s[50:51] offset:128
	s_add_i32 m0, s64, 0xffffff80
	s_nop 0
	global_load_lds_dwordx4 v134, s[50:51] offset:128
	s_waitcnt vmcnt(8)
	s_waitcnt lgkmcnt(0)
	s_barrier
	s_setprio 1
	s_waitcnt lgkmcnt(0)
	v_mfma_f32_16x16x32_bf16 v[62:65], v[154:157], v[186:189], v[62:65]
	v_mfma_f32_16x16x32_bf16 v[58:61], v[162:165], v[186:189], v[58:61]
	v_mfma_f32_16x16x32_bf16 v[50:53], v[154:157], v[194:197], v[50:53]
	v_mfma_f32_16x16x32_bf16 v[42:45], v[162:165], v[194:197], v[42:45]
	v_mfma_f32_16x16x32_bf16 v[34:37], v[154:157], v[202:205], v[34:37]
	v_mfma_f32_16x16x32_bf16 v[26:29], v[162:165], v[202:205], v[26:29]
	v_mfma_f32_16x16x32_bf16 v[18:21], v[154:157], v[210:213], v[18:21]
	v_mfma_f32_16x16x32_bf16 v[10:13], v[162:165], v[210:213], v[10:13]
	v_mfma_f32_16x16x32_bf16 v[62:65], v[158:161], v[190:193], v[62:65]
	v_mfma_f32_16x16x32_bf16 v[58:61], v[166:169], v[190:193], v[58:61]
	v_mfma_f32_16x16x32_bf16 v[50:53], v[158:161], v[198:201], v[50:53]
	v_mfma_f32_16x16x32_bf16 v[42:45], v[166:169], v[198:201], v[42:45]
	v_mfma_f32_16x16x32_bf16 v[34:37], v[158:161], v[206:209], v[34:37]
	v_mfma_f32_16x16x32_bf16 v[26:29], v[166:169], v[206:209], v[26:29]
	v_mfma_f32_16x16x32_bf16 v[18:21], v[158:161], v[214:217], v[18:21]
	v_mfma_f32_16x16x32_bf16 v[10:13], v[166:169], v[214:217], v[10:13]
	s_setprio 0
	s_setprio 1
	v_mfma_f32_16x16x32_bf16 v[54:57], v[170:173], v[186:189], v[54:57]
	v_mfma_f32_16x16x32_bf16 v[46:49], v[178:181], v[186:189], v[46:49]
	v_mfma_f32_16x16x32_bf16 v[38:41], v[170:173], v[194:197], v[38:41]
	v_mfma_f32_16x16x32_bf16 v[30:33], v[178:181], v[194:197], v[30:33]
	v_mfma_f32_16x16x32_bf16 v[22:25], v[170:173], v[202:205], v[22:25]
	v_mfma_f32_16x16x32_bf16 v[14:17], v[178:181], v[202:205], v[14:17]
	v_mfma_f32_16x16x32_bf16 v[6:9], v[170:173], v[210:213], v[6:9]
	v_mfma_f32_16x16x32_bf16 v[2:5], v[178:181], v[210:213], v[2:5]
	v_mfma_f32_16x16x32_bf16 v[54:57], v[174:177], v[190:193], v[54:57]
	v_mfma_f32_16x16x32_bf16 v[46:49], v[182:185], v[190:193], v[46:49]
	v_mfma_f32_16x16x32_bf16 v[38:41], v[174:177], v[198:201], v[38:41]
	v_mfma_f32_16x16x32_bf16 v[30:33], v[182:185], v[198:201], v[30:33]
	v_mfma_f32_16x16x32_bf16 v[22:25], v[174:177], v[206:209], v[22:25]
	v_mfma_f32_16x16x32_bf16 v[14:17], v[182:185], v[206:209], v[14:17]
	v_mfma_f32_16x16x32_bf16 v[6:9], v[174:177], v[214:217], v[6:9]
	v_mfma_f32_16x16x32_bf16 v[2:5], v[182:185], v[214:217], v[2:5]
	s_setprio 0
	s_barrier
	s_add_i32 s78, s78, 2
	s_add_u32 s40, s40, 0x100
	s_addc_u32 s41, s41, 0
	s_add_u32 s76, s76, 0x100
	s_addc_u32 s77, s77, 0
	s_cmp_gt_u32 s78, 29
	s_cbranch_scc0 .LBB0_763
	s_and_b64 vcc, exec, s[20:21]
	s_cbranch_vccz .LBB0_766
	s_barrier

; #define PG8_STAGE(bufoff, gbase, voff) do { _Pragma("unroll") for (int _i = 0; _i < 2; ++_i) \
;         __builtin_amdgcn_global_load_lds((const unsigned*)((const char*)(gbase) + (voff)[_i]), (PG8_LAS unsigned*)(lds + (bufoff) + ldsw + _i * 8192), 16, 0, 0); } while (0)
; #define PG8_LDA(dst, b, h) do { _Pragma("unroll") for (int m = 0; m < 4; ++m) _Pragma("unroll") for (int k = 0; k < 2; ++k) dst[m][k] = *(const PG8_LAS bf16x8*)(lds + PG8_SA(b, h) + aoff + m * 2048 + k * 1024); } while (0)
; #define PG8_LDB(dst, b, h) do { _Pragma("unroll") for (int n = 0; n < 2; ++n) _Pragma("unroll") for (int k = 0; k < 2; ++k) dst[n][k] = *(const PG8_LAS bf16x8*)(lds + PG8_SB(b, h) + boff + n * 2048 + k * 1024); } while (0)
; #define PG8_MMA(ai, bj, At, Bt) do { __builtin_amdgcn_s_setprio(1); _Pragma("unroll") for (int m = 0; m < 4; ++m) _Pragma("unroll") for (int n = 0; n < 2; ++n) _Pragma("unroll") for (int k = 0; k < 2; ++k) \
;         acc[ai][bj][m][n] = __builtin_amdgcn_mfma_f32_16x16x32_bf16(Bt[n][k], At[m][k], acc[ai][bj][m][n], 0, 0, 0); __builtin_amdgcn_s_setprio(0); } while (0)
; #define PG8_WAIT_V(n) asm volatile("s_waitcnt vmcnt(" #n ")" ::: "memory")
; #define PG8_WAIT_L(n) asm volatile("s_waitcnt lgkmcnt(" #n ")" ::: "memory")
; #define PG8_BAR __builtin_amdgcn_s_barrier()
; #define PG8_SCHED __builtin_amdgcn_sched_barrier(0)
; template <class Epi, class Sched, bool ALIGN_EPI = false, bool SP2 = false>
; __device__ __forceinline__ void gemm_phase(PG8_LAS unsigned char* lds, const Gemm g, const Sched& S, const Epi& E) {
;     ...
;             PG8_LDB(B0, 0, 0); PG8_LDB(B1, 0, 1); PG8_SCHED; PG8_LDA(At, 0, 0); PG8_STAGE(PG8_SA(1, 1), a1 + hstep, voffA);
;             PG8_WAIT_V(8); PG8_WAIT_L(0); PG8_BAR; PG8_MMA(0, 0, At, B0); PG8_MMA(0, 1, At, B1); PG8_BAR; PG8_SCHED;
;             PG8_LDA(At, 0, 1); PG8_STAGE(PG8_SB(0, 0), b2, voffB); PG8_STAGE(PG8_SB(0, 1), b2 + hstep, voffB); PG8_STAGE(PG8_SA(0, 0), a2, voffA);
;             PG8_WAIT_V(8); PG8_WAIT_L(0); PG8_BAR; PG8_MMA(1, 0, At, B0); PG8_MMA(1, 1, At, B1); PG8_BAR; PG8_SCHED;
.LBB0_913:
	ds_read_b128 v[156:159], v152
	ds_read_b128 v[160:163], v152 offset:1024
	ds_read_b128 v[164:167], v152 offset:2048
	ds_read_b128 v[168:171], v152 offset:3072
	ds_read_b128 v[172:175], v153
	ds_read_b128 v[176:179], v153 offset:1024
	ds_read_b128 v[180:183], v153 offset:2048
	ds_read_b128 v[184:187], v153 offset:3072
	s_add_u32 s4, s34, 0xfff80080
	s_addc_u32 s5, s35, -1
	s_cmp_eq_u32 s69, 28
	s_cselect_b32 s39, s25, s5
	s_cselect_b32 s38, s65, s4
	s_cselect_b32 s37, s23, s68
	s_cselect_b32 s36, s66, s67
	s_add_i32 m0, s31, 0xc000
	ds_read_b128 v[188:191], v154
	ds_read_b128 v[192:195], v154 offset:1024
	ds_read_b128 v[196:199], v154 offset:2048
	ds_read_b128 v[200:203], v154 offset:3072
	ds_read_b128 v[204:207], v154 offset:4096
	ds_read_b128 v[208:211], v154 offset:5120
	ds_read_b128 v[212:215], v154 offset:6144
	ds_read_b128 v[216:219], v154 offset:7168
	global_load_lds_dwordx4 v138, s[34:35]
	s_add_i32 m0, s31, 0xe000
	s_nop 0
	global_load_lds_dwordx4 v140, s[34:35]
	s_waitcnt vmcnt(8)
	s_waitcnt lgkmcnt(0)
	s_barrier
	s_setprio 1
	s_waitcnt lgkmcnt(0)
	v_mfma_f32_16x16x32_bf16 v[126:129], v[156:159], v[188:191], v[126:129]
	v_mfma_f32_16x16x32_bf16 v[122:125], v[164:167], v[188:191], v[122:125]
	v_mfma_f32_16x16x32_bf16 v[110:113], v[156:159], v[196:199], v[110:113]
	v_mfma_f32_16x16x32_bf16 v[106:109], v[164:167], v[196:199], v[106:109]
	v_mfma_f32_16x16x32_bf16 v[94:97], v[156:159], v[204:207], v[94:97]
	v_mfma_f32_16x16x32_bf16 v[90:93], v[164:167], v[204:207], v[90:93]
	v_mfma_f32_16x16x32_bf16 v[78:81], v[156:159], v[212:215], v[78:81]
	v_mfma_f32_16x16x32_bf16 v[74:77], v[164:167], v[212:215], v[74:77]
	v_mfma_f32_16x16x32_bf16 v[126:129], v[160:163], v[192:195], v[126:129]
	v_mfma_f32_16x16x32_bf16 v[122:125], v[168:171], v[192:195], v[122:125]
	v_mfma_f32_16x16x32_bf16 v[110:113], v[160:163], v[200:203], v[110:113]
	v_mfma_f32_16x16x32_bf16 v[106:109], v[168:171], v[200:203], v[106:109]
	v_mfma_f32_16x16x32_bf16 v[94:97], v[160:163], v[208:211], v[94:97]
	v_mfma_f32_16x16x32_bf16 v[90:93], v[168:171], v[208:211], v[90:93]
	v_mfma_f32_16x16x32_bf16 v[78:81], v[160:163], v[216:219], v[78:81]
	v_mfma_f32_16x16x32_bf16 v[74:77], v[168:171], v[216:219], v[74:77]
	s_setprio 0
	s_setprio 1
	v_mfma_f32_16x16x32_bf16 v[118:121], v[172:175], v[188:191], v[118:121]
	v_mfma_f32_16x16x32_bf16 v[114:117], v[180:183], v[188:191], v[114:117]
	v_mfma_f32_16x16x32_bf16 v[102:105], v[172:175], v[196:199], v[102:105]
	v_mfma_f32_16x16x32_bf16 v[98:101], v[180:183], v[196:199], v[98:101]
	v_mfma_f32_16x16x32_bf16 v[86:89], v[172:175], v[204:207], v[86:89]
	v_mfma_f32_16x16x32_bf16 v[82:85], v[180:183], v[204:207], v[82:85]
	v_mfma_f32_16x16x32_bf16 v[70:73], v[172:175], v[212:215], v[70:73]
	v_mfma_f32_16x16x32_bf16 v[66:69], v[180:183], v[212:215], v[66:69]
	v_mfma_f32_16x16x32_bf16 v[118:121], v[176:179], v[192:195], v[118:121]
	v_mfma_f32_16x16x32_bf16 v[114:117], v[184:187], v[192:195], v[114:117]
	v_mfma_f32_16x16x32_bf16 v[102:105], v[176:179], v[200:203], v[102:105]
	v_mfma_f32_16x16x32_bf16 v[98:101], v[184:187], v[200:203], v[98:101]
	v_mfma_f32_16x16x32_bf16 v[86:89], v[176:179], v[208:211], v[86:89]
	v_mfma_f32_16x16x32_bf16 v[82:85], v[184:187], v[208:211], v[82:85]
	v_mfma_f32_16x16x32_bf16 v[70:73], v[176:179], v[216:219], v[70:73]
	v_mfma_f32_16x16x32_bf16 v[66:69], v[184:187], v[216:219], v[66:69]
	s_setprio 0
	s_barrier
	s_add_i32 s4, s61, s40
	s_mov_b32 m0, s4
	ds_read_b128 v[188:191], v154 offset:16384
	ds_read_b128 v[192:195], v154 offset:17408
	ds_read_b128 v[196:199], v154 offset:18432
	ds_read_b128 v[200:203], v154 offset:19456
	ds_read_b128 v[204:207], v154 offset:20480
	ds_read_b128 v[208:211], v154 offset:21504
	ds_read_b128 v[212:215], v154 offset:22528
	ds_read_b128 v[216:219], v154 offset:23552
	global_load_lds_dwordx4 v134, s[36:37]
	s_add_i32 m0, s4, 0x2000
	s_add_u32 s4, s36, 0x80000
	s_addc_u32 s5, s37, 0
	s_add_i32 s70, s62, s40
	global_load_lds_dwordx4 v130, s[36:37]
	s_mov_b32 m0, s70
	s_nop 0
	global_load_lds_dwordx4 v134, s[4:5]
	s_add_i32 m0, s70, 0x2000
	s_nop 0
	global_load_lds_dwordx4 v130, s[4:5]
	s_waitcnt vmcnt(6)
	s_waitcnt lgkmcnt(0)
	s_barrier
	s_setprio 1
	s_waitcnt lgkmcnt(0)
	v_mfma_f32_16x16x32_bf16 v[62:65], v[156:159], v[188:191], v[62:65]
	v_mfma_f32_16x16x32_bf16 v[58:61], v[164:167], v[188:191], v[58:61]
	v_mfma_f32_16x16x32_bf16 v[46:49], v[156:159], v[196:199], v[46:49]
	v_mfma_f32_16x16x32_bf16 v[42:45], v[164:167], v[196:199], v[42:45]
	v_mfma_f32_16x16x32_bf16 v[30:33], v[156:159], v[204:207], v[30:33]
	v_mfma_f32_16x16x32_bf16 v[26:29], v[164:167], v[204:207], v[26:29]
	v_mfma_f32_16x16x32_bf16 v[14:17], v[156:159], v[212:215], v[14:17]
	v_mfma_f32_16x16x32_bf16 v[10:13], v[164:167], v[212:215], v[10:13]
	v_mfma_f32_16x16x32_bf16 v[62:65], v[160:163], v[192:195], v[62:65]
	v_mfma_f32_16x16x32_bf16 v[58:61], v[168:171], v[192:195], v[58:61]
	v_mfma_f32_16x16x32_bf16 v[46:49], v[160:163], v[200:203], v[46:49]
	v_mfma_f32_16x16x32_bf16 v[42:45], v[168:171], v[200:203], v[42:45]
	v_mfma_f32_16x16x32_bf16 v[30:33], v[160:163], v[208:211], v[30:33]
	v_mfma_f32_16x16x32_bf16 v[26:29], v[168:171], v[208:211], v[26:29]
	v_mfma_f32_16x16x32_bf16 v[14:17], v[160:163], v[216:219], v[14:17]
	v_mfma_f32_16x16x32_bf16 v[10:13], v[168:171], v[216:219], v[10:13]
	s_setprio 0
	s_setprio 1
	v_mfma_f32_16x16x32_bf16 v[54:57], v[172:175], v[188:191], v[54:57]
	v_mfma_f32_16x16x32_bf16 v[50:53], v[180:183], v[188:191], v[50:53]
	v_mfma_f32_16x16x32_bf16 v[38:41], v[172:175], v[196:199], v[38:41]
	v_mfma_f32_16x16x32_bf16 v[34:37], v[180:183], v[196:199], v[34:37]
	v_mfma_f32_16x16x32_bf16 v[22:25], v[172:175], v[204:207], v[22:25]
	v_mfma_f32_16x16x32_bf16 v[18:21], v[180:183], v[204:207], v[18:21]
	v_mfma_f32_16x16x32_bf16 v[6:9], v[172:175], v[212:215], v[6:9]
	v_mfma_f32_16x16x32_bf16 v[2:5], v[180:183], v[212:215], v[2:5]
	v_mfma_f32_16x16x32_bf16 v[54:57], v[176:179], v[192:195], v[54:57]
	v_mfma_f32_16x16x32_bf16 v[50:53], v[184:187], v[192:195], v[50:53]
	v_mfma_f32_16x16x32_bf16 v[38:41], v[176:179], v[200:203], v[38:41]
	v_mfma_f32_16x16x32_bf16 v[34:37], v[184:187], v[200:203], v[34:37]
	v_mfma_f32_16x16x32_bf16 v[22:25], v[176:179], v[208:211], v[22:25]
	v_mfma_f32_16x16x32_bf16 v[18:21], v[184:187], v[208:211], v[18:21]
	v_mfma_f32_16x16x32_bf16 v[6:9], v[176:179], v[216:219], v[6:9]
	v_mfma_f32_16x16x32_bf16 v[2:5], v[184:187], v[216:219], v[2:5]
	s_setprio 0
	s_barrier
; #define PG8_STAGE(bufoff, gbase, voff) do { _Pragma("unroll") for (int _i = 0; _i < 2; ++_i) \
;         __builtin_amdgcn_global_load_lds((const unsigned*)((const char*)(gbase) + (voff)[_i]), (PG8_LAS unsigned*)(lds + (bufoff) + ldsw + _i * 8192), 16, 0, 0); } while (0)
; #define PG8_LDA(dst, b, h) do { _Pragma("unroll") for (int m = 0; m < 4; ++m) _Pragma("unroll") for (int k = 0; k < 2; ++k) dst[m][k] = *(const PG8_LAS bf16x8*)(lds + PG8_SA(b, h) + aoff + m * 2048 + k * 1024); } while (0)
; #define PG8_LDB(dst, b, h) do { _Pragma("unroll") for (int n = 0; n < 2; ++n) _Pragma("unroll") for (int k = 0; k < 2; ++k) dst[n][k] = *(const PG8_LAS bf16x8*)(lds + PG8_SB(b, h) + boff + n * 2048 + k * 1024); } while (0)
; #define PG8_MMA(ai, bj, At, Bt) do { __builtin_amdgcn_s_setprio(1); _Pragma("unroll") for (int m = 0; m < 4; ++m) _Pragma("unroll") for (int n = 0; n < 2; ++n) _Pragma("unroll") for (int k = 0; k < 2; ++k) \
;         acc[ai][bj][m][n] = __builtin_amdgcn_mfma_f32_16x16x32_bf16(Bt[n][k], At[m][k], acc[ai][bj][m][n], 0, 0, 0); __builtin_amdgcn_s_setprio(0); } while (0)
; #define PG8_WAIT_V(n) asm volatile("s_waitcnt vmcnt(" #n ")" ::: "memory")
; #define PG8_WAIT_L(n) asm volatile("s_waitcnt lgkmcnt(" #n ")" ::: "memory")
; #define PG8_BAR __builtin_amdgcn_s_barrier()
; template <class Epi, class Sched, bool ALIGN_EPI = false, bool SP2 = false>
; __device__ __forceinline__ void gemm_phase(PG8_LAS unsigned char* lds, const Gemm g, const Sched& S, const Epi& E) {
;     ...
;         for (int t = 0; t < nt; t += 2) {
;             const bool last = (t == nt - 2);
;             const char* a1 = cA + (size_t)(t + 1) * kstep;
;             const char* a2 = last ? nA : cA + (size_t)(t + 2) * kstep; const char* b2 = last ? nB : cB + (size_t)(t + 2) * kstep;
;             const char* a3 = a2 + kstep; const char* b3 = b2 + kstep;
;     ...
;             PG8_LDB(B0, 1, 0); PG8_LDB(B1, 1, 1); PG8_SCHED; PG8_LDA(At, 1, 0); PG8_STAGE(PG8_SA(0, 1), a2 + hstep, voffA);
;             PG8_WAIT_V(8); PG8_WAIT_L(0); PG8_BAR; PG8_MMA(0, 0, At, B0); PG8_MMA(0, 1, At, B1); PG8_BAR; PG8_SCHED;
;             PG8_LDA(At, 1, 1); PG8_STAGE(PG8_SB(1, 0), b3, voffB); PG8_STAGE(PG8_SB(1, 1), b3 + hstep, voffB); PG8_STAGE(PG8_SA(1, 0), a3, voffA);
;             PG8_WAIT_V(8); PG8_WAIT_L(0); PG8_BAR; PG8_MMA(1, 0, At, B0); PG8_MMA(1, 1, At, B1); PG8_BAR; PG8_SCHED;
	s_add_i32 s70, 0, 0x18000
	v_add_u32_e32 v155, s70, v150
	s_add_i32 s71, 0, 0x1c000
	ds_read_b128 v[156:159], v155
	ds_read_b128 v[160:163], v155 offset:1024
	ds_read_b128 v[164:167], v155 offset:2048
	ds_read_b128 v[168:171], v155 offset:3072
	v_add_u32_e32 v155, s71, v150
	ds_read_b128 v[172:175], v155
	ds_read_b128 v[176:179], v155 offset:1024
	ds_read_b128 v[180:183], v155 offset:2048
	ds_read_b128 v[184:187], v155 offset:3072
	s_add_u32 s4, s38, 0x80000
	s_addc_u32 s5, s39, 0
	s_mov_b32 m0, s31
	s_nop 0
	global_load_lds_dwordx4 v136, s[38:39]
	s_mov_b32 m0, s49
	s_nop 0
	global_load_lds_dwordx4 v132, s[38:39]
	s_mov_b32 m0, s50
	ds_read_b128 v[188:191], v154 offset:32768
	ds_read_b128 v[192:195], v154 offset:33792
	ds_read_b128 v[196:199], v154 offset:34816
	ds_read_b128 v[200:203], v154 offset:35840
	ds_read_b128 v[204:207], v154 offset:36864
	ds_read_b128 v[208:211], v154 offset:37888
	ds_read_b128 v[212:215], v154 offset:38912
	ds_read_b128 v[216:219], v154 offset:39936
	global_load_lds_dwordx4 v136, s[4:5]
	s_mov_b32 m0, s51
	s_nop 0
	global_load_lds_dwordx4 v132, s[4:5]
	s_waitcnt vmcnt(8)
	s_waitcnt lgkmcnt(0)
	s_barrier
	s_setprio 1
	s_waitcnt lgkmcnt(0)
	v_mfma_f32_16x16x32_bf16 v[126:129], v[156:159], v[188:191], v[126:129]
	v_mfma_f32_16x16x32_bf16 v[122:125], v[164:167], v[188:191], v[122:125]
	v_mfma_f32_16x16x32_bf16 v[110:113], v[156:159], v[196:199], v[110:113]
	v_mfma_f32_16x16x32_bf16 v[106:109], v[164:167], v[196:199], v[106:109]
	v_mfma_f32_16x16x32_bf16 v[94:97], v[156:159], v[204:207], v[94:97]
	v_mfma_f32_16x16x32_bf16 v[90:93], v[164:167], v[204:207], v[90:93]
	v_mfma_f32_16x16x32_bf16 v[78:81], v[156:159], v[212:215], v[78:81]
	v_mfma_f32_16x16x32_bf16 v[74:77], v[164:167], v[212:215], v[74:77]
	v_mfma_f32_16x16x32_bf16 v[126:129], v[160:163], v[192:195], v[126:129]
	v_mfma_f32_16x16x32_bf16 v[122:125], v[168:171], v[192:195], v[122:125]
	v_mfma_f32_16x16x32_bf16 v[110:113], v[160:163], v[200:203], v[110:113]
	v_mfma_f32_16x16x32_bf16 v[106:109], v[168:171], v[200:203], v[106:109]
	v_mfma_f32_16x16x32_bf16 v[94:97], v[160:163], v[208:211], v[94:97]
	v_mfma_f32_16x16x32_bf16 v[90:93], v[168:171], v[208:211], v[90:93]
	v_mfma_f32_16x16x32_bf16 v[78:81], v[160:163], v[216:219], v[78:81]
	v_mfma_f32_16x16x32_bf16 v[74:77], v[168:171], v[216:219], v[74:77]
	s_setprio 0
	s_setprio 1
	v_mfma_f32_16x16x32_bf16 v[118:121], v[172:175], v[188:191], v[118:121]
	v_mfma_f32_16x16x32_bf16 v[114:117], v[180:183], v[188:191], v[114:117]
	v_mfma_f32_16x16x32_bf16 v[102:105], v[172:175], v[196:199], v[102:105]
	v_mfma_f32_16x16x32_bf16 v[98:101], v[180:183], v[196:199], v[98:101]
	v_mfma_f32_16x16x32_bf16 v[86:89], v[172:175], v[204:207], v[86:89]
	v_mfma_f32_16x16x32_bf16 v[82:85], v[180:183], v[204:207], v[82:85]
	v_mfma_f32_16x16x32_bf16 v[70:73], v[172:175], v[212:215], v[70:73]
	v_mfma_f32_16x16x32_bf16 v[66:69], v[180:183], v[212:215], v[66:69]
	v_mfma_f32_16x16x32_bf16 v[118:121], v[176:179], v[192:195], v[118:121]
	v_mfma_f32_16x16x32_bf16 v[114:117], v[184:187], v[192:195], v[114:117]
	v_mfma_f32_16x16x32_bf16 v[102:105], v[176:179], v[200:203], v[102:105]
	v_mfma_f32_16x16x32_bf16 v[98:101], v[184:187], v[200:203], v[98:101]
	v_mfma_f32_16x16x32_bf16 v[86:89], v[176:179], v[208:211], v[86:89]
	v_mfma_f32_16x16x32_bf16 v[82:85], v[184:187], v[208:211], v[82:85]
	v_mfma_f32_16x16x32_bf16 v[70:73], v[176:179], v[216:219], v[70:73]
	v_mfma_f32_16x16x32_bf16 v[66:69], v[184:187], v[216:219], v[66:69]
	s_setprio 0
	s_barrier
	s_add_i32 s4, s70, s40
	s_add_i32 m0, s4, 0xffffff80
	ds_read_b128 v[188:191], v154 offset:49152
	ds_read_b128 v[192:195], v154 offset:50176
	ds_read_b128 v[196:199], v154 offset:51200
	ds_read_b128 v[200:203], v154 offset:52224
	ds_read_b128 v[204:207], v154 offset:53248
	ds_read_b128 v[208:211], v154 offset:54272
	ds_read_b128 v[212:215], v154 offset:55296
	ds_read_b128 v[216:219], v154 offset:56320
	global_load_lds_dwordx4 v134, s[36:37] offset:128
	s_add_i32 m0, s4, 0x1f80
	s_add_u32 s4, s36, 0x80080
	s_addc_u32 s5, s37, 0
	global_load_lds_dwordx4 v130, s[36:37] offset:128
	s_add_i32 s36, s71, s40
	s_mov_b32 m0, s36
	s_nop 0
	global_load_lds_dwordx4 v134, s[4:5]
	s_add_i32 m0, s36, 0x2000
	s_nop 0
	global_load_lds_dwordx4 v130, s[4:5]
	s_add_i32 m0, s53, 0xffffff80
	s_nop 0
	global_load_lds_dwordx4 v136, s[38:39] offset:128
	s_add_i32 m0, s58, 0xffffff80
	s_nop 0
	global_load_lds_dwordx4 v132, s[38:39] offset:128
	s_waitcnt vmcnt(8)
	s_waitcnt lgkmcnt(0)
	s_barrier
	s_setprio 1
	s_waitcnt lgkmcnt(0)
	v_mfma_f32_16x16x32_bf16 v[62:65], v[156:159], v[188:191], v[62:65]
	v_mfma_f32_16x16x32_bf16 v[58:61], v[164:167], v[188:191], v[58:61]
	v_mfma_f32_16x16x32_bf16 v[46:49], v[156:159], v[196:199], v[46:49]
	v_mfma_f32_16x16x32_bf16 v[42:45], v[164:167], v[196:199], v[42:45]
	v_mfma_f32_16x16x32_bf16 v[30:33], v[156:159], v[204:207], v[30:33]
	v_mfma_f32_16x16x32_bf16 v[26:29], v[164:167], v[204:207], v[26:29]
	v_mfma_f32_16x16x32_bf16 v[14:17], v[156:159], v[212:215], v[14:17]
	v_mfma_f32_16x16x32_bf16 v[10:13], v[164:167], v[212:215], v[10:13]
	v_mfma_f32_16x16x32_bf16 v[62:65], v[160:163], v[192:195], v[62:65]
	v_mfma_f32_16x16x32_bf16 v[58:61], v[168:171], v[192:195], v[58:61]
	v_mfma_f32_16x16x32_bf16 v[46:49], v[160:163], v[200:203], v[46:49]
	v_mfma_f32_16x16x32_bf16 v[42:45], v[168:171], v[200:203], v[42:45]
	v_mfma_f32_16x16x32_bf16 v[30:33], v[160:163], v[208:211], v[30:33]
	v_mfma_f32_16x16x32_bf16 v[26:29], v[168:171], v[208:211], v[26:29]
	v_mfma_f32_16x16x32_bf16 v[14:17], v[160:163], v[216:219], v[14:17]
	v_mfma_f32_16x16x32_bf16 v[10:13], v[168:171], v[216:219], v[10:13]
	s_setprio 0
	s_setprio 1
	v_mfma_f32_16x16x32_bf16 v[54:57], v[172:175], v[188:191], v[54:57]
	v_mfma_f32_16x16x32_bf16 v[50:53], v[180:183], v[188:191], v[50:53]
	v_mfma_f32_16x16x32_bf16 v[38:41], v[172:175], v[196:199], v[38:41]
	v_mfma_f32_16x16x32_bf16 v[34:37], v[180:183], v[196:199], v[34:37]
	v_mfma_f32_16x16x32_bf16 v[22:25], v[172:175], v[204:207], v[22:25]
	v_mfma_f32_16x16x32_bf16 v[18:21], v[180:183], v[204:207], v[18:21]
	v_mfma_f32_16x16x32_bf16 v[6:9], v[172:175], v[212:215], v[6:9]
	v_mfma_f32_16x16x32_bf16 v[2:5], v[180:183], v[212:215], v[2:5]
	v_mfma_f32_16x16x32_bf16 v[54:57], v[176:179], v[192:195], v[54:57]
	v_mfma_f32_16x16x32_bf16 v[50:53], v[184:187], v[192:195], v[50:53]
	v_mfma_f32_16x16x32_bf16 v[38:41], v[176:179], v[200:203], v[38:41]
	v_mfma_f32_16x16x32_bf16 v[34:37], v[184:187], v[200:203], v[34:37]
	v_mfma_f32_16x16x32_bf16 v[22:25], v[176:179], v[208:211], v[22:25]
	v_mfma_f32_16x16x32_bf16 v[18:21], v[184:187], v[208:211], v[18:21]
	v_mfma_f32_16x16x32_bf16 v[6:9], v[176:179], v[216:219], v[6:9]
	v_mfma_f32_16x16x32_bf16 v[2:5], v[184:187], v[216:219], v[2:5]
	s_setprio 0
	s_barrier
	s_add_i32 s69, s69, 2
	s_add_u32 s34, s34, 0x100
	s_addc_u32 s35, s35, 0
	s_add_u32 s67, s67, 0x100
	s_addc_u32 s68, s68, 0
	s_cmp_gt_u32 s69, 29
	s_cbranch_scc0 .LBB0_913
	s_and_b64 vcc, exec, s[20:21]
	s_cbranch_vccz .LBB0_916
	s_barrier

; #define PG8_STAGE(bufoff, gbase, voff) do { _Pragma("unroll") for (int _i = 0; _i < 2; ++_i) \
;         __builtin_amdgcn_global_load_lds((const unsigned*)((const char*)(gbase) + (voff)[_i]), (PG8_LAS unsigned*)(lds + (bufoff) + ldsw + _i * 8192), 16, 0, 0); } while (0)
; #define PG8_LDA(dst, b, h) do { _Pragma("unroll") for (int m = 0; m < 4; ++m) _Pragma("unroll") for (int k = 0; k < 2; ++k) dst[m][k] = *(const PG8_LAS bf16x8*)(lds + PG8_SA(b, h) + aoff + m * 2048 + k * 1024); } while (0)
; #define PG8_LDB(dst, b, h) do { _Pragma("unroll") for (int n = 0; n < 2; ++n) _Pragma("unroll") for (int k = 0; k < 2; ++k) dst[n][k] = *(const PG8_LAS bf16x8*)(lds + PG8_SB(b, h) + boff + n * 2048 + k * 1024); } while (0)
; #define PG8_MMA(ai, bj, At, Bt) do { __builtin_amdgcn_s_setprio(1); _Pragma("unroll") for (int m = 0; m < 4; ++m) _Pragma("unroll") for (int n = 0; n < 2; ++n) _Pragma("unroll") for (int k = 0; k < 2; ++k) \
;         acc[ai][bj][m][n] = __builtin_amdgcn_mfma_f32_16x16x32_bf16(Bt[n][k], At[m][k], acc[ai][bj][m][n], 0, 0, 0); __builtin_amdgcn_s_setprio(0); } while (0)
; #define PG8_WAIT_V(n) asm volatile("s_waitcnt vmcnt(" #n ")" ::: "memory")
; #define PG8_WAIT_L(n) asm volatile("s_waitcnt lgkmcnt(" #n ")" ::: "memory")
; #define PG8_BAR __builtin_amdgcn_s_barrier()
; #define PG8_SCHED __builtin_amdgcn_sched_barrier(0)
; template <class Epi, class Sched, bool ALIGN_EPI = false, bool SP2 = false>
; __device__ __forceinline__ void gemm_phase(PG8_LAS unsigned char* lds, const Gemm g, const Sched& S, const Epi& E) {
;     ...
;             PG8_LDB(B0, 0, 0); PG8_LDB(B1, 0, 1); PG8_SCHED; PG8_LDA(At, 0, 0); PG8_STAGE(PG8_SA(1, 1), a1 + hstep, voffA);
;             PG8_WAIT_V(8); PG8_WAIT_L(0); PG8_BAR; PG8_MMA(0, 0, At, B0); PG8_MMA(0, 1, At, B1); PG8_BAR; PG8_SCHED;
;             PG8_LDA(At, 0, 1); PG8_STAGE(PG8_SB(0, 0), b2, voffB); PG8_STAGE(PG8_SB(0, 1), b2 + hstep, voffB); PG8_STAGE(PG8_SA(0, 0), a2, voffA);
;             PG8_WAIT_V(8); PG8_WAIT_L(0); PG8_BAR; PG8_MMA(1, 0, At, B0); PG8_MMA(1, 1, At, B1); PG8_BAR; PG8_SCHED;
.LBB0_1017:
	ds_read_b128 v[154:157], v150
	ds_read_b128 v[158:161], v150 offset:1024
	ds_read_b128 v[162:165], v150 offset:2048
	ds_read_b128 v[166:169], v150 offset:3072
	ds_read_b128 v[170:173], v151
	ds_read_b128 v[174:177], v151 offset:1024
	ds_read_b128 v[178:181], v151 offset:2048
	ds_read_b128 v[182:185], v151 offset:3072
	s_add_u32 s34, s30, 0x100
	s_addc_u32 s35, s31, 0
	s_cmpk_eq_i32 s74, 0x54
	s_cselect_b32 s39, s9, s35
	s_cselect_b32 s38, s8, s34
	s_cselect_b32 s37, s29, s73
	s_cselect_b32 s36, s28, s72
	s_add_i32 m0, s49, 0xc000
	ds_read_b128 v[186:189], v152
	ds_read_b128 v[190:193], v152 offset:1024
	ds_read_b128 v[194:197], v152 offset:2048
	ds_read_b128 v[198:201], v152 offset:3072
	ds_read_b128 v[202:205], v152 offset:4096
	ds_read_b128 v[206:209], v152 offset:5120
	ds_read_b128 v[210:213], v152 offset:6144
	ds_read_b128 v[214:217], v152 offset:7168
	global_load_lds_dwordx4 v138, s[30:31]
	s_add_i32 m0, s49, 0xe000
	s_nop 0
	global_load_lds_dwordx4 v140, s[30:31]
	s_waitcnt vmcnt(8)
	s_waitcnt lgkmcnt(0)
	s_barrier
	s_setprio 1
	s_waitcnt lgkmcnt(0)
	v_mfma_f32_16x16x32_bf16 v[126:129], v[154:157], v[186:189], v[126:129]
	v_mfma_f32_16x16x32_bf16 v[122:125], v[162:165], v[186:189], v[122:125]
	v_mfma_f32_16x16x32_bf16 v[114:117], v[154:157], v[194:197], v[114:117]
	v_mfma_f32_16x16x32_bf16 v[106:109], v[162:165], v[194:197], v[106:109]
	v_mfma_f32_16x16x32_bf16 v[98:101], v[154:157], v[202:205], v[98:101]
	v_mfma_f32_16x16x32_bf16 v[90:93], v[162:165], v[202:205], v[90:93]
	v_mfma_f32_16x16x32_bf16 v[82:85], v[154:157], v[210:213], v[82:85]
	v_mfma_f32_16x16x32_bf16 v[74:77], v[162:165], v[210:213], v[74:77]
	v_mfma_f32_16x16x32_bf16 v[126:129], v[158:161], v[190:193], v[126:129]
	v_mfma_f32_16x16x32_bf16 v[122:125], v[166:169], v[190:193], v[122:125]
	v_mfma_f32_16x16x32_bf16 v[114:117], v[158:161], v[198:201], v[114:117]
	v_mfma_f32_16x16x32_bf16 v[106:109], v[166:169], v[198:201], v[106:109]
	v_mfma_f32_16x16x32_bf16 v[98:101], v[158:161], v[206:209], v[98:101]
	v_mfma_f32_16x16x32_bf16 v[90:93], v[166:169], v[206:209], v[90:93]
	v_mfma_f32_16x16x32_bf16 v[82:85], v[158:161], v[214:217], v[82:85]
	v_mfma_f32_16x16x32_bf16 v[74:77], v[166:169], v[214:217], v[74:77]
	s_setprio 0
	s_setprio 1
	v_mfma_f32_16x16x32_bf16 v[118:121], v[170:173], v[186:189], v[118:121]
	v_mfma_f32_16x16x32_bf16 v[110:113], v[178:181], v[186:189], v[110:113]
	v_mfma_f32_16x16x32_bf16 v[102:105], v[170:173], v[194:197], v[102:105]
	v_mfma_f32_16x16x32_bf16 v[94:97], v[178:181], v[194:197], v[94:97]
	v_mfma_f32_16x16x32_bf16 v[86:89], v[170:173], v[202:205], v[86:89]
	v_mfma_f32_16x16x32_bf16 v[78:81], v[178:181], v[202:205], v[78:81]
	v_mfma_f32_16x16x32_bf16 v[70:73], v[170:173], v[210:213], v[70:73]
	v_mfma_f32_16x16x32_bf16 v[66:69], v[178:181], v[210:213], v[66:69]
	v_mfma_f32_16x16x32_bf16 v[118:121], v[174:177], v[190:193], v[118:121]
	v_mfma_f32_16x16x32_bf16 v[110:113], v[182:185], v[190:193], v[110:113]
	v_mfma_f32_16x16x32_bf16 v[102:105], v[174:177], v[198:201], v[102:105]
	v_mfma_f32_16x16x32_bf16 v[94:97], v[182:185], v[198:201], v[94:97]
	v_mfma_f32_16x16x32_bf16 v[86:89], v[174:177], v[206:209], v[86:89]
	v_mfma_f32_16x16x32_bf16 v[78:81], v[182:185], v[206:209], v[78:81]
	v_mfma_f32_16x16x32_bf16 v[70:73], v[174:177], v[214:217], v[70:73]
	v_mfma_f32_16x16x32_bf16 v[66:69], v[182:185], v[214:217], v[66:69]
	s_setprio 0
	s_barrier
	s_add_i32 s4, s62, s48
	s_mov_b32 m0, s4
	ds_read_b128 v[186:189], v152 offset:16384
	ds_read_b128 v[190:193], v152 offset:17408
	ds_read_b128 v[194:197], v152 offset:18432
	ds_read_b128 v[198:201], v152 offset:19456
	ds_read_b128 v[202:205], v152 offset:20480
	ds_read_b128 v[206:209], v152 offset:21504
	ds_read_b128 v[210:213], v152 offset:22528
	ds_read_b128 v[214:217], v152 offset:23552
	global_load_lds_dwordx4 v132, s[36:37]
	s_add_i32 m0, s4, 0x2000
	s_add_u32 s4, s36, 0x160000
	s_addc_u32 s5, s37, 0
	s_add_i32 s30, s63, s48
	global_load_lds_dwordx4 v136, s[36:37]
	s_mov_b32 m0, s30
	s_nop 0
	global_load_lds_dwordx4 v132, s[4:5]
	s_add_i32 m0, s30, 0x2000
	s_nop 0
	global_load_lds_dwordx4 v136, s[4:5]
	s_waitcnt vmcnt(6)
	s_waitcnt lgkmcnt(0)
	s_barrier
	s_setprio 1
	s_waitcnt lgkmcnt(0)
	v_mfma_f32_16x16x32_bf16 v[62:65], v[154:157], v[186:189], v[62:65]
	v_mfma_f32_16x16x32_bf16 v[58:61], v[162:165], v[186:189], v[58:61]
	v_mfma_f32_16x16x32_bf16 v[50:53], v[154:157], v[194:197], v[50:53]
	v_mfma_f32_16x16x32_bf16 v[42:45], v[162:165], v[194:197], v[42:45]
	v_mfma_f32_16x16x32_bf16 v[34:37], v[154:157], v[202:205], v[34:37]
	v_mfma_f32_16x16x32_bf16 v[26:29], v[162:165], v[202:205], v[26:29]
	v_mfma_f32_16x16x32_bf16 v[18:21], v[154:157], v[210:213], v[18:21]
	v_mfma_f32_16x16x32_bf16 v[10:13], v[162:165], v[210:213], v[10:13]
	v_mfma_f32_16x16x32_bf16 v[62:65], v[158:161], v[190:193], v[62:65]
	v_mfma_f32_16x16x32_bf16 v[58:61], v[166:169], v[190:193], v[58:61]
	v_mfma_f32_16x16x32_bf16 v[50:53], v[158:161], v[198:201], v[50:53]
	v_mfma_f32_16x16x32_bf16 v[42:45], v[166:169], v[198:201], v[42:45]
	v_mfma_f32_16x16x32_bf16 v[34:37], v[158:161], v[206:209], v[34:37]
	v_mfma_f32_16x16x32_bf16 v[26:29], v[166:169], v[206:209], v[26:29]
	v_mfma_f32_16x16x32_bf16 v[18:21], v[158:161], v[214:217], v[18:21]
	v_mfma_f32_16x16x32_bf16 v[10:13], v[166:169], v[214:217], v[10:13]
	s_setprio 0
	s_setprio 1
	v_mfma_f32_16x16x32_bf16 v[54:57], v[170:173], v[186:189], v[54:57]
	v_mfma_f32_16x16x32_bf16 v[46:49], v[178:181], v[186:189], v[46:49]
	v_mfma_f32_16x16x32_bf16 v[38:41], v[170:173], v[194:197], v[38:41]
	v_mfma_f32_16x16x32_bf16 v[30:33], v[178:181], v[194:197], v[30:33]
	v_mfma_f32_16x16x32_bf16 v[22:25], v[170:173], v[202:205], v[22:25]
	v_mfma_f32_16x16x32_bf16 v[14:17], v[178:181], v[202:205], v[14:17]
	v_mfma_f32_16x16x32_bf16 v[6:9], v[170:173], v[210:213], v[6:9]
	v_mfma_f32_16x16x32_bf16 v[2:5], v[178:181], v[210:213], v[2:5]
	v_mfma_f32_16x16x32_bf16 v[54:57], v[174:177], v[190:193], v[54:57]
	v_mfma_f32_16x16x32_bf16 v[46:49], v[182:185], v[190:193], v[46:49]
	v_mfma_f32_16x16x32_bf16 v[38:41], v[174:177], v[198:201], v[38:41]
	v_mfma_f32_16x16x32_bf16 v[30:33], v[182:185], v[198:201], v[30:33]
	v_mfma_f32_16x16x32_bf16 v[22:25], v[174:177], v[206:209], v[22:25]
	v_mfma_f32_16x16x32_bf16 v[14:17], v[182:185], v[206:209], v[14:17]
	v_mfma_f32_16x16x32_bf16 v[6:9], v[174:177], v[214:217], v[6:9]
	v_mfma_f32_16x16x32_bf16 v[2:5], v[182:185], v[214:217], v[2:5]
	s_setprio 0
	s_barrier
; #define PG8_STAGE(bufoff, gbase, voff) do { _Pragma("unroll") for (int _i = 0; _i < 2; ++_i) \
;         __builtin_amdgcn_global_load_lds((const unsigned*)((const char*)(gbase) + (voff)[_i]), (PG8_LAS unsigned*)(lds + (bufoff) + ldsw + _i * 8192), 16, 0, 0); } while (0)
; #define PG8_LDA(dst, b, h) do { _Pragma("unroll") for (int m = 0; m < 4; ++m) _Pragma("unroll") for (int k = 0; k < 2; ++k) dst[m][k] = *(const PG8_LAS bf16x8*)(lds + PG8_SA(b, h) + aoff + m * 2048 + k * 1024); } while (0)
; #define PG8_LDB(dst, b, h) do { _Pragma("unroll") for (int n = 0; n < 2; ++n) _Pragma("unroll") for (int k = 0; k < 2; ++k) dst[n][k] = *(const PG8_LAS bf16x8*)(lds + PG8_SB(b, h) + boff + n * 2048 + k * 1024); } while (0)
; #define PG8_MMA(ai, bj, At, Bt) do { __builtin_amdgcn_s_setprio(1); _Pragma("unroll") for (int m = 0; m < 4; ++m) _Pragma("unroll") for (int n = 0; n < 2; ++n) _Pragma("unroll") for (int k = 0; k < 2; ++k) \
;         acc[ai][bj][m][n] = __builtin_amdgcn_mfma_f32_16x16x32_bf16(Bt[n][k], At[m][k], acc[ai][bj][m][n], 0, 0, 0); __builtin_amdgcn_s_setprio(0); } while (0)
; #define PG8_WAIT_V(n) asm volatile("s_waitcnt vmcnt(" #n ")" ::: "memory")
; #define PG8_WAIT_L(n) asm volatile("s_waitcnt lgkmcnt(" #n ")" ::: "memory")
; #define PG8_BAR __builtin_amdgcn_s_barrier()
; #define PG8_SCHED __builtin_amdgcn_sched_barrier(0)
; template <class Epi, class Sched, bool ALIGN_EPI = false, bool SP2 = false>
; __device__ __forceinline__ void gemm_phase(PG8_LAS unsigned char* lds, const Gemm g, const Sched& S, const Epi& E) {
;     ...
;             PG8_LDB(B0, 1, 0); PG8_LDB(B1, 1, 1); PG8_SCHED; PG8_LDA(At, 1, 0); PG8_STAGE(PG8_SA(0, 1), a2 + hstep, voffA);
;             PG8_WAIT_V(8); PG8_WAIT_L(0); PG8_BAR; PG8_MMA(0, 0, At, B0); PG8_MMA(0, 1, At, B1); PG8_BAR; PG8_SCHED;
;             PG8_LDA(At, 1, 1); PG8_STAGE(PG8_SB(1, 0), b3, voffB); PG8_STAGE(PG8_SB(1, 1), b3 + hstep, voffB); PG8_STAGE(PG8_SA(1, 0), a3, voffA);
;             PG8_WAIT_V(8); PG8_WAIT_L(0); PG8_BAR; PG8_MMA(1, 0, At, B0); PG8_MMA(1, 1, At, B1); PG8_BAR; PG8_SCHED;
	s_add_i32 s30, 0, 0x18000
	v_add_u32_e32 v153, s30, v148
	s_add_i32 s31, 0, 0x1c000
	ds_read_b128 v[154:157], v153
	ds_read_b128 v[158:161], v153 offset:1024
	ds_read_b128 v[162:165], v153 offset:2048
	ds_read_b128 v[166:169], v153 offset:3072
	v_add_u32_e32 v153, s31, v148
	ds_read_b128 v[170:173], v153
	ds_read_b128 v[174:177], v153 offset:1024
	ds_read_b128 v[178:181], v153 offset:2048
	ds_read_b128 v[182:185], v153 offset:3072
	s_add_u32 s4, s38, 0x160000
	s_addc_u32 s5, s39, 0
	s_mov_b32 m0, s49
	s_nop 0
	global_load_lds_dwordx4 v130, s[38:39]
	s_mov_b32 m0, s50
	s_nop 0
	global_load_lds_dwordx4 v134, s[38:39]
	s_mov_b32 m0, s51
	ds_read_b128 v[186:189], v152 offset:32768
	ds_read_b128 v[190:193], v152 offset:33792
	ds_read_b128 v[194:197], v152 offset:34816
	ds_read_b128 v[198:201], v152 offset:35840
	ds_read_b128 v[202:205], v152 offset:36864
	ds_read_b128 v[206:209], v152 offset:37888
	ds_read_b128 v[210:213], v152 offset:38912
	ds_read_b128 v[214:217], v152 offset:39936
	global_load_lds_dwordx4 v130, s[4:5]
	s_mov_b32 m0, s52
	s_nop 0
	global_load_lds_dwordx4 v134, s[4:5]
	s_waitcnt vmcnt(8)
	s_waitcnt lgkmcnt(0)
	s_barrier
	s_setprio 1
	s_waitcnt lgkmcnt(0)
	v_mfma_f32_16x16x32_bf16 v[126:129], v[154:157], v[186:189], v[126:129]
	v_mfma_f32_16x16x32_bf16 v[122:125], v[162:165], v[186:189], v[122:125]
	v_mfma_f32_16x16x32_bf16 v[114:117], v[154:157], v[194:197], v[114:117]
	v_mfma_f32_16x16x32_bf16 v[106:109], v[162:165], v[194:197], v[106:109]
	v_mfma_f32_16x16x32_bf16 v[98:101], v[154:157], v[202:205], v[98:101]
	v_mfma_f32_16x16x32_bf16 v[90:93], v[162:165], v[202:205], v[90:93]
	v_mfma_f32_16x16x32_bf16 v[82:85], v[154:157], v[210:213], v[82:85]
	v_mfma_f32_16x16x32_bf16 v[74:77], v[162:165], v[210:213], v[74:77]
	v_mfma_f32_16x16x32_bf16 v[126:129], v[158:161], v[190:193], v[126:129]
	v_mfma_f32_16x16x32_bf16 v[122:125], v[166:169], v[190:193], v[122:125]
	v_mfma_f32_16x16x32_bf16 v[114:117], v[158:161], v[198:201], v[114:117]
	v_mfma_f32_16x16x32_bf16 v[106:109], v[166:169], v[198:201], v[106:109]
	v_mfma_f32_16x16x32_bf16 v[98:101], v[158:161], v[206:209], v[98:101]
	v_mfma_f32_16x16x32_bf16 v[90:93], v[166:169], v[206:209], v[90:93]
	v_mfma_f32_16x16x32_bf16 v[82:85], v[158:161], v[214:217], v[82:85]
	v_mfma_f32_16x16x32_bf16 v[74:77], v[166:169], v[214:217], v[74:77]
	s_setprio 0
	s_setprio 1
	v_mfma_f32_16x16x32_bf16 v[118:121], v[170:173], v[186:189], v[118:121]
	v_mfma_f32_16x16x32_bf16 v[110:113], v[178:181], v[186:189], v[110:113]
	v_mfma_f32_16x16x32_bf16 v[102:105], v[170:173], v[194:197], v[102:105]
	v_mfma_f32_16x16x32_bf16 v[94:97], v[178:181], v[194:197], v[94:97]
	v_mfma_f32_16x16x32_bf16 v[86:89], v[170:173], v[202:205], v[86:89]
	v_mfma_f32_16x16x32_bf16 v[78:81], v[178:181], v[202:205], v[78:81]
	v_mfma_f32_16x16x32_bf16 v[70:73], v[170:173], v[210:213], v[70:73]
	v_mfma_f32_16x16x32_bf16 v[66:69], v[178:181], v[210:213], v[66:69]
	v_mfma_f32_16x16x32_bf16 v[118:121], v[174:177], v[190:193], v[118:121]
	v_mfma_f32_16x16x32_bf16 v[110:113], v[182:185], v[190:193], v[110:113]
	v_mfma_f32_16x16x32_bf16 v[102:105], v[174:177], v[198:201], v[102:105]
	v_mfma_f32_16x16x32_bf16 v[94:97], v[182:185], v[198:201], v[94:97]
	v_mfma_f32_16x16x32_bf16 v[86:89], v[174:177], v[206:209], v[86:89]
	v_mfma_f32_16x16x32_bf16 v[78:81], v[182:185], v[206:209], v[78:81]
	v_mfma_f32_16x16x32_bf16 v[70:73], v[174:177], v[214:217], v[70:73]
	v_mfma_f32_16x16x32_bf16 v[66:69], v[182:185], v[214:217], v[66:69]
	s_setprio 0
	s_barrier
	s_add_i32 s4, s30, s48
	s_add_i32 m0, s4, 0xffffff80
	ds_read_b128 v[186:189], v152 offset:49152
	ds_read_b128 v[190:193], v152 offset:50176
	ds_read_b128 v[194:197], v152 offset:51200
	ds_read_b128 v[198:201], v152 offset:52224
	ds_read_b128 v[202:205], v152 offset:53248
	ds_read_b128 v[206:209], v152 offset:54272
	ds_read_b128 v[210:213], v152 offset:55296
	ds_read_b128 v[214:217], v152 offset:56320
	global_load_lds_dwordx4 v132, s[36:37] offset:128
	s_add_i32 m0, s4, 0x1f80
	s_add_u32 s4, s36, 0x160080
	s_addc_u32 s5, s37, 0
	s_add_i32 s30, s31, s48
	global_load_lds_dwordx4 v136, s[36:37] offset:128
	s_mov_b32 m0, s30
	s_nop 0
	global_load_lds_dwordx4 v132, s[4:5]
	s_add_i32 m0, s30, 0x2000
	s_nop 0
	global_load_lds_dwordx4 v136, s[4:5]
	s_add_i32 m0, s58, 0xffffff80
	s_nop 0
	global_load_lds_dwordx4 v130, s[38:39] offset:128
	s_add_i32 m0, s59, 0xffffff80
	s_nop 0
	global_load_lds_dwordx4 v134, s[38:39] offset:128
	s_waitcnt vmcnt(8)
	s_waitcnt lgkmcnt(0)
	s_barrier
	s_setprio 1
	s_waitcnt lgkmcnt(0)
	v_mfma_f32_16x16x32_bf16 v[62:65], v[154:157], v[186:189], v[62:65]
	v_mfma_f32_16x16x32_bf16 v[58:61], v[162:165], v[186:189], v[58:61]
	v_mfma_f32_16x16x32_bf16 v[50:53], v[154:157], v[194:197], v[50:53]
	v_mfma_f32_16x16x32_bf16 v[42:45], v[162:165], v[194:197], v[42:45]
	v_mfma_f32_16x16x32_bf16 v[34:37], v[154:157], v[202:205], v[34:37]
	v_mfma_f32_16x16x32_bf16 v[26:29], v[162:165], v[202:205], v[26:29]
	v_mfma_f32_16x16x32_bf16 v[18:21], v[154:157], v[210:213], v[18:21]
	v_mfma_f32_16x16x32_bf16 v[10:13], v[162:165], v[210:213], v[10:13]
	v_mfma_f32_16x16x32_bf16 v[62:65], v[158:161], v[190:193], v[62:65]
	v_mfma_f32_16x16x32_bf16 v[58:61], v[166:169], v[190:193], v[58:61]
	v_mfma_f32_16x16x32_bf16 v[50:53], v[158:161], v[198:201], v[50:53]
	v_mfma_f32_16x16x32_bf16 v[42:45], v[166:169], v[198:201], v[42:45]
	v_mfma_f32_16x16x32_bf16 v[34:37], v[158:161], v[206:209], v[34:37]
	v_mfma_f32_16x16x32_bf16 v[26:29], v[166:169], v[206:209], v[26:29]
	v_mfma_f32_16x16x32_bf16 v[18:21], v[158:161], v[214:217], v[18:21]
	v_mfma_f32_16x16x32_bf16 v[10:13], v[166:169], v[214:217], v[10:13]
	s_setprio 0
	s_setprio 1
	v_mfma_f32_16x16x32_bf16 v[54:57], v[170:173], v[186:189], v[54:57]
	v_mfma_f32_16x16x32_bf16 v[46:49], v[178:181], v[186:189], v[46:49]
	v_mfma_f32_16x16x32_bf16 v[38:41], v[170:173], v[194:197], v[38:41]
	v_mfma_f32_16x16x32_bf16 v[30:33], v[178:181], v[194:197], v[30:33]
	v_mfma_f32_16x16x32_bf16 v[22:25], v[170:173], v[202:205], v[22:25]
	v_mfma_f32_16x16x32_bf16 v[14:17], v[178:181], v[202:205], v[14:17]
	v_mfma_f32_16x16x32_bf16 v[6:9], v[170:173], v[210:213], v[6:9]
	v_mfma_f32_16x16x32_bf16 v[2:5], v[178:181], v[210:213], v[2:5]
	v_mfma_f32_16x16x32_bf16 v[54:57], v[174:177], v[190:193], v[54:57]
	v_mfma_f32_16x16x32_bf16 v[46:49], v[182:185], v[190:193], v[46:49]
	v_mfma_f32_16x16x32_bf16 v[38:41], v[174:177], v[198:201], v[38:41]
	v_mfma_f32_16x16x32_bf16 v[30:33], v[182:185], v[198:201], v[30:33]
	v_mfma_f32_16x16x32_bf16 v[22:25], v[174:177], v[206:209], v[22:25]
	v_mfma_f32_16x16x32_bf16 v[14:17], v[182:185], v[206:209], v[14:17]
	v_mfma_f32_16x16x32_bf16 v[6:9], v[174:177], v[214:217], v[6:9]
	v_mfma_f32_16x16x32_bf16 v[2:5], v[182:185], v[214:217], v[2:5]
	s_setprio 0
	s_barrier
	s_add_i32 s74, s74, 2
	s_add_u32 s72, s72, 0x100
	s_addc_u32 s73, s73, 0
	s_cmpk_gt_u32 s74, 0x55
	s_mov_b64 s[30:31], s[34:35]
	s_cbranch_scc0 .LBB0_1017
	s_and_b64 vcc, exec, s[18:19]
	s_cbranch_vccz .LBB0_1020
	s_barrier
